# GEMM K-loops: MFMAs inside each 8-group reordered so consecutive ones change exactly one source operand (same accumulator order, bit-identical results)
# baseline (speedup 1.0000x reference)
.LBB0_345:
	s_add_u32 s42, s56, 0xfffc0080
	s_addc_u32 s43, s57, -1
	s_add_i32 s59, 0, 0x10000
	s_cmp_eq_u32 s58, 12
	s_cselect_b32 s55, s17, s43
	s_cselect_b32 s54, s19, s42
	v_add_u32_e32 v138, s59, v141
	s_cselect_b32 s43, s15, s53
	s_cselect_b32 s42, s50, s51
	s_add_i32 s62, 0, 0x14000
	ds_read_b128 v[154:157], v138
	ds_read_b128 v[158:161], v138 offset:1024
	ds_read_b128 v[162:165], v138 offset:2048
	ds_read_b128 v[166:169], v138 offset:3072
	v_add_u32_e32 v138, s62, v141
	ds_read_b128 v[170:173], v138
	ds_read_b128 v[174:177], v138 offset:1024
	ds_read_b128 v[178:181], v138 offset:2048
	ds_read_b128 v[204:207], v138 offset:3072
	v_lshl_add_u64 v[138:139], s[56:57], 0, v[134:135]
	s_add_i32 m0, s38, 0xc000
	ds_read_b128 v[208:211], v143
	ds_read_b128 v[212:215], v143 offset:1024
	ds_read_b128 v[216:219], v143 offset:2048
	ds_read_b128 v[220:223], v143 offset:3072
	ds_read_b128 v[224:227], v143 offset:4096
	ds_read_b128 v[228:231], v143 offset:5120
	ds_read_b128 v[232:235], v143 offset:6144
	ds_read_b128 v[236:239], v143 offset:7168
	global_load_lds_dwordx4 v[138:139], off
	v_lshl_add_u64 v[138:139], s[56:57], 0, v[136:137]
	s_add_i32 m0, s38, 0xe000
	s_nop 0
	global_load_lds_dwordx4 v[138:139], off
	s_waitcnt vmcnt(8)
	s_waitcnt lgkmcnt(0)
	s_barrier
	s_setprio 1
	s_waitcnt lgkmcnt(0)
	v_mfma_f32_16x16x32_bf16 v[124:127], v[154:157], v[208:211], v[124:127]
	v_mfma_f32_16x16x32_bf16 v[116:119], v[162:165], v[208:211], v[116:119]
	v_mfma_f32_16x16x32_bf16 v[100:103], v[162:165], v[216:219], v[100:103]
	v_mfma_f32_16x16x32_bf16 v[108:111], v[154:157], v[216:219], v[108:111]
	v_mfma_f32_16x16x32_bf16 v[92:95], v[154:157], v[224:227], v[92:95]
	v_mfma_f32_16x16x32_bf16 v[84:87], v[162:165], v[224:227], v[84:87]
	v_mfma_f32_16x16x32_bf16 v[68:71], v[162:165], v[232:235], v[68:71]
	v_mfma_f32_16x16x32_bf16 v[76:79], v[154:157], v[232:235], v[76:79]
	v_mfma_f32_16x16x32_bf16 v[124:127], v[158:161], v[212:215], v[124:127]
	v_mfma_f32_16x16x32_bf16 v[116:119], v[166:169], v[212:215], v[116:119]
	v_mfma_f32_16x16x32_bf16 v[100:103], v[166:169], v[220:223], v[100:103]
	v_mfma_f32_16x16x32_bf16 v[108:111], v[158:161], v[220:223], v[108:111]
	v_mfma_f32_16x16x32_bf16 v[92:95], v[158:161], v[228:231], v[92:95]
	v_mfma_f32_16x16x32_bf16 v[84:87], v[166:169], v[228:231], v[84:87]
	v_mfma_f32_16x16x32_bf16 v[68:71], v[166:169], v[236:239], v[68:71]
	v_mfma_f32_16x16x32_bf16 v[76:79], v[158:161], v[236:239], v[76:79]
	s_setprio 0
	s_setprio 1
	v_mfma_f32_16x16x32_bf16 v[120:123], v[170:173], v[208:211], v[120:123]
	v_mfma_f32_16x16x32_bf16 v[112:115], v[178:181], v[208:211], v[112:115]
	v_mfma_f32_16x16x32_bf16 v[96:99], v[178:181], v[216:219], v[96:99]
	v_mfma_f32_16x16x32_bf16 v[104:107], v[170:173], v[216:219], v[104:107]
	v_mfma_f32_16x16x32_bf16 v[88:91], v[170:173], v[224:227], v[88:91]
	v_mfma_f32_16x16x32_bf16 v[80:83], v[178:181], v[224:227], v[80:83]
	v_mfma_f32_16x16x32_bf16 v[64:67], v[178:181], v[232:235], v[64:67]
	v_mfma_f32_16x16x32_bf16 v[72:75], v[170:173], v[232:235], v[72:75]
	v_mfma_f32_16x16x32_bf16 v[120:123], v[174:177], v[212:215], v[120:123]
	v_mfma_f32_16x16x32_bf16 v[112:115], v[204:207], v[212:215], v[112:115]
	v_mfma_f32_16x16x32_bf16 v[96:99], v[204:207], v[220:223], v[96:99]
	v_mfma_f32_16x16x32_bf16 v[104:107], v[174:177], v[220:223], v[104:107]
	v_mfma_f32_16x16x32_bf16 v[88:91], v[174:177], v[228:231], v[88:91]
	v_mfma_f32_16x16x32_bf16 v[80:83], v[204:207], v[228:231], v[80:83]
	v_mfma_f32_16x16x32_bf16 v[64:67], v[204:207], v[236:239], v[64:67]
	v_mfma_f32_16x16x32_bf16 v[72:75], v[174:177], v[236:239], v[72:75]
	s_setprio 0
	s_barrier
	s_add_i32 s59, s59, s36
	v_lshl_add_u64 v[138:139], s[42:43], 0, v[144:145]
	s_mov_b32 m0, s59
	ds_read_b128 v[208:211], v143 offset:16384
	ds_read_b128 v[212:215], v143 offset:17408
	ds_read_b128 v[216:219], v143 offset:18432
	ds_read_b128 v[220:223], v143 offset:19456
	ds_read_b128 v[224:227], v143 offset:20480
	ds_read_b128 v[228:231], v143 offset:21504
	ds_read_b128 v[232:235], v143 offset:22528
	ds_read_b128 v[236:239], v143 offset:23552
	global_load_lds_dwordx4 v[138:139], off
	s_add_i32 m0, s59, 0x2000
	s_add_u32 s60, s42, 0x40000
	v_lshl_add_u64 v[240:241], s[42:43], 0, v[128:129]
	s_addc_u32 s61, s43, 0
	s_add_i32 s59, s62, s36
	global_load_lds_dwordx4 v[240:241], off
	v_lshl_add_u64 v[242:243], s[60:61], 0, v[144:145]
	s_mov_b32 m0, s59
	v_lshl_add_u64 v[244:245], s[54:55], 0, v[130:131]
	global_load_lds_dwordx4 v[242:243], off
	v_lshl_add_u64 v[242:243], s[60:61], 0, v[128:129]
	s_add_i32 m0, s59, 0x2000
	s_nop 0
	global_load_lds_dwordx4 v[242:243], off
	v_lshl_add_u64 v[242:243], s[54:55], 0, v[132:133]
	s_mov_b32 m0, s38
	s_nop 0
	global_load_lds_dwordx4 v[242:243], off
	s_mov_b32 m0, s40
	s_nop 0
	global_load_lds_dwordx4 v[244:245], off
	s_waitcnt vmcnt(8)
	s_waitcnt lgkmcnt(0)
	s_barrier
	s_setprio 1
	s_waitcnt lgkmcnt(0)
	v_mfma_f32_16x16x32_bf16 v[60:63], v[154:157], v[208:211], v[60:63]
	v_mfma_f32_16x16x32_bf16 v[52:55], v[162:165], v[208:211], v[52:55]
	v_mfma_f32_16x16x32_bf16 v[36:39], v[162:165], v[216:219], v[36:39]
	v_mfma_f32_16x16x32_bf16 v[44:47], v[154:157], v[216:219], v[44:47]
	v_mfma_f32_16x16x32_bf16 v[28:31], v[154:157], v[224:227], v[28:31]
	v_mfma_f32_16x16x32_bf16 v[20:23], v[162:165], v[224:227], v[20:23]
	v_mfma_f32_16x16x32_bf16 v[4:7], v[162:165], v[232:235], v[4:7]
	v_mfma_f32_16x16x32_bf16 v[12:15], v[154:157], v[232:235], v[12:15]
	v_mfma_f32_16x16x32_bf16 v[60:63], v[158:161], v[212:215], v[60:63]
	v_mfma_f32_16x16x32_bf16 v[52:55], v[166:169], v[212:215], v[52:55]
	v_mfma_f32_16x16x32_bf16 v[36:39], v[166:169], v[220:223], v[36:39]
	v_mfma_f32_16x16x32_bf16 v[44:47], v[158:161], v[220:223], v[44:47]
	v_mfma_f32_16x16x32_bf16 v[28:31], v[158:161], v[228:231], v[28:31]
	v_mfma_f32_16x16x32_bf16 v[20:23], v[166:169], v[228:231], v[20:23]
	v_mfma_f32_16x16x32_bf16 v[4:7], v[166:169], v[236:239], v[4:7]
	v_mfma_f32_16x16x32_bf16 v[12:15], v[158:161], v[236:239], v[12:15]
	s_setprio 0
	s_setprio 1
	v_mfma_f32_16x16x32_bf16 v[56:59], v[170:173], v[208:211], v[56:59]
	v_mfma_f32_16x16x32_bf16 v[48:51], v[178:181], v[208:211], v[48:51]
	v_mfma_f32_16x16x32_bf16 v[32:35], v[178:181], v[216:219], v[32:35]
	v_mfma_f32_16x16x32_bf16 v[40:43], v[170:173], v[216:219], v[40:43]
	v_mfma_f32_16x16x32_bf16 v[24:27], v[170:173], v[224:227], v[24:27]
	v_mfma_f32_16x16x32_bf16 v[16:19], v[178:181], v[224:227], v[16:19]
	v_mfma_f32_16x16x32_bf16 v[0:3], v[178:181], v[232:235], v[0:3]
	v_mfma_f32_16x16x32_bf16 v[8:11], v[170:173], v[232:235], v[8:11]
	v_mfma_f32_16x16x32_bf16 v[56:59], v[174:177], v[212:215], v[56:59]
	v_mfma_f32_16x16x32_bf16 v[48:51], v[204:207], v[212:215], v[48:51]
	v_mfma_f32_16x16x32_bf16 v[32:35], v[204:207], v[220:223], v[32:35]
	v_mfma_f32_16x16x32_bf16 v[40:43], v[174:177], v[220:223], v[40:43]
	v_mfma_f32_16x16x32_bf16 v[24:27], v[174:177], v[228:231], v[24:27]
	v_mfma_f32_16x16x32_bf16 v[16:19], v[204:207], v[228:231], v[16:19]
	v_mfma_f32_16x16x32_bf16 v[0:3], v[204:207], v[236:239], v[0:3]
	v_mfma_f32_16x16x32_bf16 v[8:11], v[174:177], v[236:239], v[8:11]
	s_setprio 0
	s_barrier
	s_add_i32 s59, 0, 0x18000
	s_add_i32 s60, 0, 0x1c000
	v_add_u32_e32 v166, s59, v141
	v_add_u32_e32 v190, s60, v141
	ds_read_b128 v[154:157], v166
	ds_read_b128 v[158:161], v166 offset:1024
	ds_read_b128 v[162:165], v166 offset:2048
	ds_read_b128 v[166:169], v166 offset:3072
	ds_read_b128 v[170:173], v190
	ds_read_b128 v[174:177], v190 offset:1024
	ds_read_b128 v[178:181], v190 offset:2048
	ds_read_b128 v[204:207], v190 offset:3072
	s_add_u32 s54, s54, 0x40000
	s_addc_u32 s55, s55, 0
	s_mov_b32 m0, s41
	v_lshl_add_u64 v[246:247], s[54:55], 0, v[132:133]
	ds_read_b128 v[208:211], v143 offset:32768
	ds_read_b128 v[212:215], v143 offset:33792
	ds_read_b128 v[216:219], v143 offset:34816
	ds_read_b128 v[220:223], v143 offset:35840
	ds_read_b128 v[224:227], v143 offset:36864
	ds_read_b128 v[228:231], v143 offset:37888
	ds_read_b128 v[232:235], v143 offset:38912
	ds_read_b128 v[236:239], v143 offset:39936
	global_load_lds_dwordx4 v[246:247], off
	v_lshl_add_u64 v[246:247], s[54:55], 0, v[130:131]
	s_mov_b32 m0, s44
	s_nop 0
	global_load_lds_dwordx4 v[246:247], off
	s_waitcnt vmcnt(8)
	s_waitcnt lgkmcnt(0)
	s_barrier
	s_setprio 1
	s_waitcnt lgkmcnt(0)
	v_mfma_f32_16x16x32_bf16 v[124:127], v[154:157], v[208:211], v[124:127]
	v_mfma_f32_16x16x32_bf16 v[116:119], v[162:165], v[208:211], v[116:119]
	v_mfma_f32_16x16x32_bf16 v[100:103], v[162:165], v[216:219], v[100:103]
	v_mfma_f32_16x16x32_bf16 v[108:111], v[154:157], v[216:219], v[108:111]
	v_mfma_f32_16x16x32_bf16 v[92:95], v[154:157], v[224:227], v[92:95]
	v_mfma_f32_16x16x32_bf16 v[84:87], v[162:165], v[224:227], v[84:87]
	v_mfma_f32_16x16x32_bf16 v[68:71], v[162:165], v[232:235], v[68:71]
	v_mfma_f32_16x16x32_bf16 v[76:79], v[154:157], v[232:235], v[76:79]
	v_mfma_f32_16x16x32_bf16 v[124:127], v[158:161], v[212:215], v[124:127]
	v_mfma_f32_16x16x32_bf16 v[116:119], v[166:169], v[212:215], v[116:119]
	v_mfma_f32_16x16x32_bf16 v[100:103], v[166:169], v[220:223], v[100:103]
	v_mfma_f32_16x16x32_bf16 v[108:111], v[158:161], v[220:223], v[108:111]
	v_mfma_f32_16x16x32_bf16 v[92:95], v[158:161], v[228:231], v[92:95]
	v_mfma_f32_16x16x32_bf16 v[84:87], v[166:169], v[228:231], v[84:87]
	v_mfma_f32_16x16x32_bf16 v[68:71], v[166:169], v[236:239], v[68:71]
	v_mfma_f32_16x16x32_bf16 v[76:79], v[158:161], v[236:239], v[76:79]
	s_setprio 0
	s_setprio 1
	v_mfma_f32_16x16x32_bf16 v[120:123], v[170:173], v[208:211], v[120:123]
	v_mfma_f32_16x16x32_bf16 v[112:115], v[178:181], v[208:211], v[112:115]
	v_mfma_f32_16x16x32_bf16 v[96:99], v[178:181], v[216:219], v[96:99]
	v_mfma_f32_16x16x32_bf16 v[104:107], v[170:173], v[216:219], v[104:107]
	v_mfma_f32_16x16x32_bf16 v[88:91], v[170:173], v[224:227], v[88:91]
	v_mfma_f32_16x16x32_bf16 v[80:83], v[178:181], v[224:227], v[80:83]
	v_mfma_f32_16x16x32_bf16 v[64:67], v[178:181], v[232:235], v[64:67]
	v_mfma_f32_16x16x32_bf16 v[72:75], v[170:173], v[232:235], v[72:75]
	v_mfma_f32_16x16x32_bf16 v[120:123], v[174:177], v[212:215], v[120:123]
	v_mfma_f32_16x16x32_bf16 v[112:115], v[204:207], v[212:215], v[112:115]
	v_mfma_f32_16x16x32_bf16 v[96:99], v[204:207], v[220:223], v[96:99]
	v_mfma_f32_16x16x32_bf16 v[104:107], v[174:177], v[220:223], v[104:107]
	v_mfma_f32_16x16x32_bf16 v[88:91], v[174:177], v[228:231], v[88:91]
	v_mfma_f32_16x16x32_bf16 v[80:83], v[204:207], v[228:231], v[80:83]
	v_mfma_f32_16x16x32_bf16 v[64:67], v[204:207], v[236:239], v[64:67]
	v_mfma_f32_16x16x32_bf16 v[72:75], v[174:177], v[236:239], v[72:75]
	s_setprio 0
	s_barrier
	s_add_i32 s54, s59, s36
	v_lshl_add_u64 v[138:139], v[138:139], 0, s[48:49]
	s_mov_b32 m0, s54
	ds_read_b128 v[208:211], v143 offset:49152
	ds_read_b128 v[212:215], v143 offset:50176
	ds_read_b128 v[216:219], v143 offset:51200
	ds_read_b128 v[220:223], v143 offset:52224
	ds_read_b128 v[224:227], v143 offset:53248
	ds_read_b128 v[228:231], v143 offset:54272
	ds_read_b128 v[232:235], v143 offset:55296
	ds_read_b128 v[236:239], v143 offset:56320
	global_load_lds_dwordx4 v[138:139], off
	s_add_i32 m0, s54, 0x2000
	s_add_u32 s42, s42, 0x40080
	v_lshl_add_u64 v[138:139], v[240:241], 0, s[48:49]
	s_addc_u32 s43, s43, 0
	s_add_i32 s54, s60, s36
	global_load_lds_dwordx4 v[138:139], off
	v_lshl_add_u64 v[138:139], s[42:43], 0, v[144:145]
	s_mov_b32 m0, s54
	s_nop 0
	global_load_lds_dwordx4 v[138:139], off
	v_lshl_add_u64 v[138:139], s[42:43], 0, v[128:129]
	s_add_i32 m0, s54, 0x2000
	s_nop 0
	global_load_lds_dwordx4 v[138:139], off
	v_lshl_add_u64 v[138:139], v[242:243], 0, s[48:49]
	s_mov_b32 m0, s45
	s_nop 0
	global_load_lds_dwordx4 v[138:139], off
	v_lshl_add_u64 v[138:139], v[244:245], 0, s[48:49]
	s_mov_b32 m0, s46
	s_nop 0
	global_load_lds_dwordx4 v[138:139], off
	s_waitcnt vmcnt(8)
	s_waitcnt lgkmcnt(0)
	s_barrier
	s_setprio 1
	s_waitcnt lgkmcnt(0)
	v_mfma_f32_16x16x32_bf16 v[60:63], v[154:157], v[208:211], v[60:63]
	v_mfma_f32_16x16x32_bf16 v[52:55], v[162:165], v[208:211], v[52:55]
	v_mfma_f32_16x16x32_bf16 v[36:39], v[162:165], v[216:219], v[36:39]
	v_mfma_f32_16x16x32_bf16 v[44:47], v[154:157], v[216:219], v[44:47]
	v_mfma_f32_16x16x32_bf16 v[28:31], v[154:157], v[224:227], v[28:31]
	v_mfma_f32_16x16x32_bf16 v[20:23], v[162:165], v[224:227], v[20:23]
	v_mfma_f32_16x16x32_bf16 v[4:7], v[162:165], v[232:235], v[4:7]
	v_mfma_f32_16x16x32_bf16 v[12:15], v[154:157], v[232:235], v[12:15]
	v_mfma_f32_16x16x32_bf16 v[60:63], v[158:161], v[212:215], v[60:63]
	v_mfma_f32_16x16x32_bf16 v[52:55], v[166:169], v[212:215], v[52:55]
	v_mfma_f32_16x16x32_bf16 v[36:39], v[166:169], v[220:223], v[36:39]
	v_mfma_f32_16x16x32_bf16 v[44:47], v[158:161], v[220:223], v[44:47]
	v_mfma_f32_16x16x32_bf16 v[28:31], v[158:161], v[228:231], v[28:31]
	v_mfma_f32_16x16x32_bf16 v[20:23], v[166:169], v[228:231], v[20:23]
	v_mfma_f32_16x16x32_bf16 v[4:7], v[166:169], v[236:239], v[4:7]
	v_mfma_f32_16x16x32_bf16 v[12:15], v[158:161], v[236:239], v[12:15]
	s_setprio 0
	s_setprio 1
	v_mfma_f32_16x16x32_bf16 v[56:59], v[170:173], v[208:211], v[56:59]
	v_mfma_f32_16x16x32_bf16 v[48:51], v[178:181], v[208:211], v[48:51]
	v_mfma_f32_16x16x32_bf16 v[32:35], v[178:181], v[216:219], v[32:35]
	v_mfma_f32_16x16x32_bf16 v[40:43], v[170:173], v[216:219], v[40:43]
	v_mfma_f32_16x16x32_bf16 v[24:27], v[170:173], v[224:227], v[24:27]
	v_mfma_f32_16x16x32_bf16 v[16:19], v[178:181], v[224:227], v[16:19]
	v_mfma_f32_16x16x32_bf16 v[0:3], v[178:181], v[232:235], v[0:3]
	v_mfma_f32_16x16x32_bf16 v[8:11], v[170:173], v[232:235], v[8:11]
	v_mfma_f32_16x16x32_bf16 v[56:59], v[174:177], v[212:215], v[56:59]
	v_mfma_f32_16x16x32_bf16 v[48:51], v[204:207], v[212:215], v[48:51]
	v_mfma_f32_16x16x32_bf16 v[32:35], v[204:207], v[220:223], v[32:35]
	v_mfma_f32_16x16x32_bf16 v[40:43], v[174:177], v[220:223], v[40:43]
	v_mfma_f32_16x16x32_bf16 v[24:27], v[174:177], v[228:231], v[24:27]
	v_mfma_f32_16x16x32_bf16 v[16:19], v[204:207], v[228:231], v[16:19]
	v_mfma_f32_16x16x32_bf16 v[0:3], v[204:207], v[236:239], v[0:3]
	v_mfma_f32_16x16x32_bf16 v[8:11], v[174:177], v[236:239], v[8:11]
	s_setprio 0
	s_barrier
	s_add_i32 s58, s58, 2
	s_add_u32 s56, s56, 0x100
	s_addc_u32 s57, s57, 0
	s_add_u32 s51, s51, 0x100
	s_addc_u32 s53, s53, 0
	s_cmp_gt_u32 s58, 13
	s_cbranch_scc0 .LBB0_345
	s_and_b64 vcc, exec, s[6:7]
	s_cbranch_vccz .LBB0_348
	s_barrier

.LBB0_459:
	s_add_u32 s20, s18, 0x100
	s_addc_u32 s21, s19, 0
	s_add_i32 s58, 0, 0x10000
	s_cmp_eq_u32 s57, 18
	s_cselect_b32 s25, s5, s21
	s_cselect_b32 s24, s4, s20
	v_add_u32_e32 v140, s58, v143
	s_cselect_b32 s23, s15, s56
	s_cselect_b32 s22, s14, s17
	s_add_i32 s59, 0, 0x14000
	ds_read_b128 v[156:159], v140
	ds_read_b128 v[160:163], v140 offset:1024
	ds_read_b128 v[164:167], v140 offset:2048
	ds_read_b128 v[168:171], v140 offset:3072
	v_add_u32_e32 v140, s59, v143
	ds_read_b128 v[172:175], v140
	ds_read_b128 v[176:179], v140 offset:1024
	ds_read_b128 v[204:207], v140 offset:2048
	ds_read_b128 v[208:211], v140 offset:3072
	v_lshl_add_u64 v[140:141], s[18:19], 0, v[136:137]
	s_add_i32 m0, s37, 0xc000
	ds_read_b128 v[212:215], v154
	ds_read_b128 v[216:219], v154 offset:1024
	ds_read_b128 v[220:223], v154 offset:2048
	ds_read_b128 v[224:227], v154 offset:3072
	ds_read_b128 v[228:231], v154 offset:4096
	ds_read_b128 v[232:235], v154 offset:5120
	ds_read_b128 v[236:239], v154 offset:6144
	ds_read_b128 v[240:243], v154 offset:7168
	global_load_lds_dwordx4 v[140:141], off
	v_lshl_add_u64 v[140:141], s[18:19], 0, v[138:139]
	s_add_i32 m0, s37, 0xe000
	s_nop 0
	global_load_lds_dwordx4 v[140:141], off
	s_waitcnt vmcnt(8)
	s_waitcnt lgkmcnt(0)
	s_barrier
	s_setprio 1
	s_waitcnt lgkmcnt(0)
	v_mfma_f32_16x16x32_bf16 v[124:127], v[156:159], v[212:215], v[124:127]
	v_mfma_f32_16x16x32_bf16 v[120:123], v[164:167], v[212:215], v[120:123]
	v_mfma_f32_16x16x32_bf16 v[108:111], v[164:167], v[220:223], v[108:111]
	v_mfma_f32_16x16x32_bf16 v[116:119], v[156:159], v[220:223], v[116:119]
	v_mfma_f32_16x16x32_bf16 v[100:103], v[156:159], v[228:231], v[100:103]
	v_mfma_f32_16x16x32_bf16 v[92:95], v[164:167], v[228:231], v[92:95]
	v_mfma_f32_16x16x32_bf16 v[76:79], v[164:167], v[236:239], v[76:79]
	v_mfma_f32_16x16x32_bf16 v[84:87], v[156:159], v[236:239], v[84:87]
	v_mfma_f32_16x16x32_bf16 v[124:127], v[160:163], v[216:219], v[124:127]
	v_mfma_f32_16x16x32_bf16 v[120:123], v[168:171], v[216:219], v[120:123]
	v_mfma_f32_16x16x32_bf16 v[108:111], v[168:171], v[224:227], v[108:111]
	v_mfma_f32_16x16x32_bf16 v[116:119], v[160:163], v[224:227], v[116:119]
	v_mfma_f32_16x16x32_bf16 v[100:103], v[160:163], v[232:235], v[100:103]
	v_mfma_f32_16x16x32_bf16 v[92:95], v[168:171], v[232:235], v[92:95]
	v_mfma_f32_16x16x32_bf16 v[76:79], v[168:171], v[240:243], v[76:79]
	v_mfma_f32_16x16x32_bf16 v[84:87], v[160:163], v[240:243], v[84:87]
	s_setprio 0
	s_setprio 1
	v_mfma_f32_16x16x32_bf16 v[112:115], v[172:175], v[212:215], v[112:115]
	v_mfma_f32_16x16x32_bf16 v[104:107], v[204:207], v[212:215], v[104:107]
	v_mfma_f32_16x16x32_bf16 v[88:91], v[204:207], v[220:223], v[88:91]
	v_mfma_f32_16x16x32_bf16 v[96:99], v[172:175], v[220:223], v[96:99]
	v_mfma_f32_16x16x32_bf16 v[80:83], v[172:175], v[228:231], v[80:83]
	v_mfma_f32_16x16x32_bf16 v[72:75], v[204:207], v[228:231], v[72:75]
	v_mfma_f32_16x16x32_bf16 v[64:67], v[204:207], v[236:239], v[64:67]
	v_mfma_f32_16x16x32_bf16 v[68:71], v[172:175], v[236:239], v[68:71]
	v_mfma_f32_16x16x32_bf16 v[112:115], v[176:179], v[216:219], v[112:115]
	v_mfma_f32_16x16x32_bf16 v[104:107], v[208:211], v[216:219], v[104:107]
	v_mfma_f32_16x16x32_bf16 v[88:91], v[208:211], v[224:227], v[88:91]
	v_mfma_f32_16x16x32_bf16 v[96:99], v[176:179], v[224:227], v[96:99]
	v_mfma_f32_16x16x32_bf16 v[80:83], v[176:179], v[232:235], v[80:83]
	v_mfma_f32_16x16x32_bf16 v[72:75], v[208:211], v[232:235], v[72:75]
	v_mfma_f32_16x16x32_bf16 v[64:67], v[208:211], v[240:243], v[64:67]
	v_mfma_f32_16x16x32_bf16 v[68:71], v[176:179], v[240:243], v[68:71]
	s_setprio 0
	s_barrier
	s_add_i32 s18, s58, s36
	v_lshl_add_u64 v[140:141], s[22:23], 0, v[130:131]
	s_mov_b32 m0, s18
	ds_read_b128 v[212:215], v154 offset:16384
	ds_read_b128 v[216:219], v154 offset:17408
	ds_read_b128 v[220:223], v154 offset:18432
	ds_read_b128 v[224:227], v154 offset:19456
	ds_read_b128 v[228:231], v154 offset:20480
	ds_read_b128 v[232:235], v154 offset:21504
	ds_read_b128 v[236:239], v154 offset:22528
	ds_read_b128 v[240:243], v154 offset:23552
	global_load_lds_dwordx4 v[140:141], off
	s_add_i32 m0, s18, 0x2000
	s_add_u32 s18, s22, 0xb0000
	v_lshl_add_u64 v[180:181], s[22:23], 0, v[134:135]
	s_addc_u32 s19, s23, 0
	s_add_i32 s58, s59, s36
	global_load_lds_dwordx4 v[180:181], off
	v_lshl_add_u64 v[244:245], s[18:19], 0, v[130:131]
	s_mov_b32 m0, s58
	v_lshl_add_u64 v[246:247], s[24:25], 0, v[132:133]
	global_load_lds_dwordx4 v[244:245], off
	v_lshl_add_u64 v[244:245], s[18:19], 0, v[134:135]
	s_add_i32 m0, s58, 0x2000
	s_nop 0
	global_load_lds_dwordx4 v[244:245], off
	v_lshl_add_u64 v[244:245], s[24:25], 0, v[128:129]
	s_mov_b32 m0, s37
	s_nop 0
	global_load_lds_dwordx4 v[244:245], off
	s_mov_b32 m0, s40
	s_nop 0
	global_load_lds_dwordx4 v[246:247], off
	s_waitcnt vmcnt(8)
	s_waitcnt lgkmcnt(0)
	s_barrier
	s_setprio 1
	s_waitcnt lgkmcnt(0)
	v_mfma_f32_16x16x32_bf16 v[60:63], v[156:159], v[212:215], v[60:63]
	v_mfma_f32_16x16x32_bf16 v[56:59], v[164:167], v[212:215], v[56:59]
	v_mfma_f32_16x16x32_bf16 v[44:47], v[164:167], v[220:223], v[44:47]
	v_mfma_f32_16x16x32_bf16 v[52:55], v[156:159], v[220:223], v[52:55]
	v_mfma_f32_16x16x32_bf16 v[36:39], v[156:159], v[228:231], v[36:39]
	v_mfma_f32_16x16x32_bf16 v[28:31], v[164:167], v[228:231], v[28:31]
	v_mfma_f32_16x16x32_bf16 v[12:15], v[164:167], v[236:239], v[12:15]
	v_mfma_f32_16x16x32_bf16 v[20:23], v[156:159], v[236:239], v[20:23]
	v_mfma_f32_16x16x32_bf16 v[60:63], v[160:163], v[216:219], v[60:63]
	v_mfma_f32_16x16x32_bf16 v[56:59], v[168:171], v[216:219], v[56:59]
	v_mfma_f32_16x16x32_bf16 v[44:47], v[168:171], v[224:227], v[44:47]
	v_mfma_f32_16x16x32_bf16 v[52:55], v[160:163], v[224:227], v[52:55]
	v_mfma_f32_16x16x32_bf16 v[36:39], v[160:163], v[232:235], v[36:39]
	v_mfma_f32_16x16x32_bf16 v[28:31], v[168:171], v[232:235], v[28:31]
	v_mfma_f32_16x16x32_bf16 v[12:15], v[168:171], v[240:243], v[12:15]
	v_mfma_f32_16x16x32_bf16 v[20:23], v[160:163], v[240:243], v[20:23]
	s_setprio 0
	s_setprio 1
	v_mfma_f32_16x16x32_bf16 v[48:51], v[172:175], v[212:215], v[48:51]
	v_mfma_f32_16x16x32_bf16 v[40:43], v[204:207], v[212:215], v[40:43]
	v_mfma_f32_16x16x32_bf16 v[24:27], v[204:207], v[220:223], v[24:27]
	v_mfma_f32_16x16x32_bf16 v[32:35], v[172:175], v[220:223], v[32:35]
	v_mfma_f32_16x16x32_bf16 v[16:19], v[172:175], v[228:231], v[16:19]
	v_mfma_f32_16x16x32_bf16 v[8:11], v[204:207], v[228:231], v[8:11]
	v_mfma_f32_16x16x32_bf16 v[0:3], v[204:207], v[236:239], v[0:3]
	v_mfma_f32_16x16x32_bf16 v[4:7], v[172:175], v[236:239], v[4:7]
	v_mfma_f32_16x16x32_bf16 v[48:51], v[176:179], v[216:219], v[48:51]
	v_mfma_f32_16x16x32_bf16 v[40:43], v[208:211], v[216:219], v[40:43]
	v_mfma_f32_16x16x32_bf16 v[24:27], v[208:211], v[224:227], v[24:27]
	v_mfma_f32_16x16x32_bf16 v[32:35], v[176:179], v[224:227], v[32:35]
	v_mfma_f32_16x16x32_bf16 v[16:19], v[176:179], v[232:235], v[16:19]
	v_mfma_f32_16x16x32_bf16 v[8:11], v[208:211], v[232:235], v[8:11]
	v_mfma_f32_16x16x32_bf16 v[0:3], v[208:211], v[240:243], v[0:3]
	v_mfma_f32_16x16x32_bf16 v[4:7], v[176:179], v[240:243], v[4:7]
	s_setprio 0
	s_barrier
	s_add_i32 s58, 0, 0x18000
	v_add_u32_e32 v155, s58, v143
	s_add_i32 s59, 0, 0x1c000
	ds_read_b128 v[156:159], v155
	ds_read_b128 v[160:163], v155 offset:1024
	ds_read_b128 v[164:167], v155 offset:2048
	ds_read_b128 v[168:171], v155 offset:3072
	v_add_u32_e32 v155, s59, v143
	ds_read_b128 v[172:175], v155
	ds_read_b128 v[176:179], v155 offset:1024
	ds_read_b128 v[204:207], v155 offset:2048
	ds_read_b128 v[208:211], v155 offset:3072
	s_add_u32 s18, s24, 0xb0000
	s_addc_u32 s19, s25, 0
	s_mov_b32 m0, s41
	v_lshl_add_u64 v[248:249], s[18:19], 0, v[128:129]
	ds_read_b128 v[212:215], v154 offset:32768
	ds_read_b128 v[216:219], v154 offset:33792
	ds_read_b128 v[220:223], v154 offset:34816
	ds_read_b128 v[224:227], v154 offset:35840
	ds_read_b128 v[228:231], v154 offset:36864
	ds_read_b128 v[232:235], v154 offset:37888
	ds_read_b128 v[236:239], v154 offset:38912
	ds_read_b128 v[240:243], v154 offset:39936
	global_load_lds_dwordx4 v[248:249], off
	v_lshl_add_u64 v[248:249], s[18:19], 0, v[132:133]
	s_mov_b32 m0, s42
	s_nop 0
	global_load_lds_dwordx4 v[248:249], off
	s_waitcnt vmcnt(8)
	s_waitcnt lgkmcnt(0)
	s_barrier
	s_setprio 1
	s_waitcnt lgkmcnt(0)
	v_mfma_f32_16x16x32_bf16 v[124:127], v[156:159], v[212:215], v[124:127]
	v_mfma_f32_16x16x32_bf16 v[120:123], v[164:167], v[212:215], v[120:123]
	v_mfma_f32_16x16x32_bf16 v[108:111], v[164:167], v[220:223], v[108:111]
	v_mfma_f32_16x16x32_bf16 v[116:119], v[156:159], v[220:223], v[116:119]
	v_mfma_f32_16x16x32_bf16 v[100:103], v[156:159], v[228:231], v[100:103]
	v_mfma_f32_16x16x32_bf16 v[92:95], v[164:167], v[228:231], v[92:95]
	v_mfma_f32_16x16x32_bf16 v[76:79], v[164:167], v[236:239], v[76:79]
	v_mfma_f32_16x16x32_bf16 v[84:87], v[156:159], v[236:239], v[84:87]
	v_mfma_f32_16x16x32_bf16 v[124:127], v[160:163], v[216:219], v[124:127]
	v_mfma_f32_16x16x32_bf16 v[120:123], v[168:171], v[216:219], v[120:123]
	v_mfma_f32_16x16x32_bf16 v[108:111], v[168:171], v[224:227], v[108:111]
	v_mfma_f32_16x16x32_bf16 v[116:119], v[160:163], v[224:227], v[116:119]
	v_mfma_f32_16x16x32_bf16 v[100:103], v[160:163], v[232:235], v[100:103]
	v_mfma_f32_16x16x32_bf16 v[92:95], v[168:171], v[232:235], v[92:95]
	v_mfma_f32_16x16x32_bf16 v[76:79], v[168:171], v[240:243], v[76:79]
	v_mfma_f32_16x16x32_bf16 v[84:87], v[160:163], v[240:243], v[84:87]
	s_setprio 0
	s_setprio 1
	v_mfma_f32_16x16x32_bf16 v[112:115], v[172:175], v[212:215], v[112:115]
	v_mfma_f32_16x16x32_bf16 v[104:107], v[204:207], v[212:215], v[104:107]
	v_mfma_f32_16x16x32_bf16 v[88:91], v[204:207], v[220:223], v[88:91]
	v_mfma_f32_16x16x32_bf16 v[96:99], v[172:175], v[220:223], v[96:99]
	v_mfma_f32_16x16x32_bf16 v[80:83], v[172:175], v[228:231], v[80:83]
	v_mfma_f32_16x16x32_bf16 v[72:75], v[204:207], v[228:231], v[72:75]
	v_mfma_f32_16x16x32_bf16 v[64:67], v[204:207], v[236:239], v[64:67]
	v_mfma_f32_16x16x32_bf16 v[68:71], v[172:175], v[236:239], v[68:71]
	v_mfma_f32_16x16x32_bf16 v[112:115], v[176:179], v[216:219], v[112:115]
	v_mfma_f32_16x16x32_bf16 v[104:107], v[208:211], v[216:219], v[104:107]
	v_mfma_f32_16x16x32_bf16 v[88:91], v[208:211], v[224:227], v[88:91]
	v_mfma_f32_16x16x32_bf16 v[96:99], v[176:179], v[224:227], v[96:99]
	v_mfma_f32_16x16x32_bf16 v[80:83], v[176:179], v[232:235], v[80:83]
	v_mfma_f32_16x16x32_bf16 v[72:75], v[208:211], v[232:235], v[72:75]
	v_mfma_f32_16x16x32_bf16 v[64:67], v[208:211], v[240:243], v[64:67]
	v_mfma_f32_16x16x32_bf16 v[68:71], v[176:179], v[240:243], v[68:71]
	s_setprio 0
	s_barrier
	s_add_i32 s18, s58, s36
	v_lshl_add_u64 v[140:141], v[140:141], 0, s[48:49]
	s_mov_b32 m0, s18
	ds_read_b128 v[212:215], v154 offset:49152
	ds_read_b128 v[216:219], v154 offset:50176
	ds_read_b128 v[220:223], v154 offset:51200
	ds_read_b128 v[224:227], v154 offset:52224
	ds_read_b128 v[228:231], v154 offset:53248
	ds_read_b128 v[232:235], v154 offset:54272
	ds_read_b128 v[236:239], v154 offset:55296
	ds_read_b128 v[240:243], v154 offset:56320
	global_load_lds_dwordx4 v[140:141], off
	s_add_i32 m0, s18, 0x2000
	s_add_u32 s18, s22, 0xb0080
	v_lshl_add_u64 v[140:141], v[180:181], 0, s[48:49]
	s_addc_u32 s19, s23, 0
	s_add_i32 s22, s59, s36
	global_load_lds_dwordx4 v[140:141], off
	v_lshl_add_u64 v[140:141], s[18:19], 0, v[130:131]
	s_mov_b32 m0, s22
	s_nop 0
	global_load_lds_dwordx4 v[140:141], off
	v_lshl_add_u64 v[140:141], s[18:19], 0, v[134:135]
	s_add_i32 m0, s22, 0x2000
	s_nop 0
	global_load_lds_dwordx4 v[140:141], off
	v_lshl_add_u64 v[140:141], v[244:245], 0, s[48:49]
	s_mov_b32 m0, s43
	s_nop 0
	global_load_lds_dwordx4 v[140:141], off
	v_lshl_add_u64 v[140:141], v[246:247], 0, s[48:49]
	s_mov_b32 m0, s44
	s_nop 0
	global_load_lds_dwordx4 v[140:141], off
	s_waitcnt vmcnt(8)
	s_waitcnt lgkmcnt(0)
	s_barrier
	s_setprio 1
	s_waitcnt lgkmcnt(0)
	v_mfma_f32_16x16x32_bf16 v[60:63], v[156:159], v[212:215], v[60:63]
	v_mfma_f32_16x16x32_bf16 v[56:59], v[164:167], v[212:215], v[56:59]
	v_mfma_f32_16x16x32_bf16 v[44:47], v[164:167], v[220:223], v[44:47]
	v_mfma_f32_16x16x32_bf16 v[52:55], v[156:159], v[220:223], v[52:55]
	v_mfma_f32_16x16x32_bf16 v[36:39], v[156:159], v[228:231], v[36:39]
	v_mfma_f32_16x16x32_bf16 v[28:31], v[164:167], v[228:231], v[28:31]
	v_mfma_f32_16x16x32_bf16 v[12:15], v[164:167], v[236:239], v[12:15]
	v_mfma_f32_16x16x32_bf16 v[20:23], v[156:159], v[236:239], v[20:23]
	v_mfma_f32_16x16x32_bf16 v[60:63], v[160:163], v[216:219], v[60:63]
	v_mfma_f32_16x16x32_bf16 v[56:59], v[168:171], v[216:219], v[56:59]
	v_mfma_f32_16x16x32_bf16 v[44:47], v[168:171], v[224:227], v[44:47]
	v_mfma_f32_16x16x32_bf16 v[52:55], v[160:163], v[224:227], v[52:55]
	v_mfma_f32_16x16x32_bf16 v[36:39], v[160:163], v[232:235], v[36:39]
	v_mfma_f32_16x16x32_bf16 v[28:31], v[168:171], v[232:235], v[28:31]
	v_mfma_f32_16x16x32_bf16 v[12:15], v[168:171], v[240:243], v[12:15]
	v_mfma_f32_16x16x32_bf16 v[20:23], v[160:163], v[240:243], v[20:23]
	s_setprio 0
	s_setprio 1
	v_mfma_f32_16x16x32_bf16 v[48:51], v[172:175], v[212:215], v[48:51]
	v_mfma_f32_16x16x32_bf16 v[40:43], v[204:207], v[212:215], v[40:43]
	v_mfma_f32_16x16x32_bf16 v[24:27], v[204:207], v[220:223], v[24:27]
	v_mfma_f32_16x16x32_bf16 v[32:35], v[172:175], v[220:223], v[32:35]
	v_mfma_f32_16x16x32_bf16 v[16:19], v[172:175], v[228:231], v[16:19]
	v_mfma_f32_16x16x32_bf16 v[8:11], v[204:207], v[228:231], v[8:11]
	v_mfma_f32_16x16x32_bf16 v[0:3], v[204:207], v[236:239], v[0:3]
	v_mfma_f32_16x16x32_bf16 v[4:7], v[172:175], v[236:239], v[4:7]
	v_mfma_f32_16x16x32_bf16 v[48:51], v[176:179], v[216:219], v[48:51]
	v_mfma_f32_16x16x32_bf16 v[40:43], v[208:211], v[216:219], v[40:43]
	v_mfma_f32_16x16x32_bf16 v[24:27], v[208:211], v[224:227], v[24:27]
	v_mfma_f32_16x16x32_bf16 v[32:35], v[176:179], v[224:227], v[32:35]
	v_mfma_f32_16x16x32_bf16 v[16:19], v[176:179], v[232:235], v[16:19]
	v_mfma_f32_16x16x32_bf16 v[8:11], v[208:211], v[232:235], v[8:11]
	v_mfma_f32_16x16x32_bf16 v[0:3], v[208:211], v[240:243], v[0:3]
	v_mfma_f32_16x16x32_bf16 v[4:7], v[176:179], v[240:243], v[4:7]
	s_setprio 0
	s_barrier
	s_add_i32 s57, s57, 2
	s_add_u32 s17, s17, 0x100
	s_addc_u32 s56, s56, 0
	s_cmp_gt_u32 s57, 19
	s_mov_b64 s[18:19], s[20:21]
	s_cbranch_scc0 .LBB0_459
	s_and_b64 vcc, exec, s[12:13]
	s_cbranch_vccz .LBB0_462
	s_barrier

.LBB0_594:
	s_add_u32 s37, s4, 0xfffc0080
	s_addc_u32 s38, s5, -1
	s_add_i32 s40, 0, 0x10000
	s_cmp_eq_u32 s36, 12
	s_cselect_b32 s55, s7, s38
	s_cselect_b32 s54, s9, s37
	v_add_u32_e32 v144, s40, v141
	s_cselect_b32 s43, s26, s31
	s_cselect_b32 s42, s27, s30
	s_add_i32 s37, 0, 0x14000
	ds_read_b128 v[128:131], v144
	ds_read_b128 v[166:169], v144 offset:1024
	ds_read_b128 v[170:173], v144 offset:2048
	ds_read_b128 v[174:177], v144 offset:3072
	v_add_u32_e32 v144, s37, v141
	ds_read_b128 v[178:181], v144
	ds_read_b128 v[204:207], v144 offset:1024
	ds_read_b128 v[208:211], v144 offset:2048
	ds_read_b128 v[212:215], v144 offset:3072
	v_lshl_add_u64 v[248:249], s[4:5], 0, v[162:163]
	s_add_i32 m0, s87, 0xc000
	ds_read_b128 v[216:219], v155
	ds_read_b128 v[220:223], v155 offset:1024
	ds_read_b128 v[224:227], v155 offset:2048
	ds_read_b128 v[228:231], v155 offset:3072
	ds_read_b128 v[232:235], v155 offset:4096
	ds_read_b128 v[236:239], v155 offset:5120
	ds_read_b128 v[240:243], v155 offset:6144
	ds_read_b128 v[244:247], v155 offset:7168
	global_load_lds_dwordx4 v[248:249], off
	v_lshl_add_u64 v[248:249], s[4:5], 0, v[164:165]
	s_add_i32 m0, s87, 0xe000
	s_nop 0
	global_load_lds_dwordx4 v[248:249], off
	s_waitcnt vmcnt(8)
	s_waitcnt lgkmcnt(0)
	s_barrier
	s_setprio 1
	s_waitcnt lgkmcnt(0)
	v_mfma_f32_16x16x32_bf16 v[124:127], v[128:131], v[216:219], v[124:127]
	v_mfma_f32_16x16x32_bf16 v[120:123], v[170:173], v[216:219], v[120:123]
	v_mfma_f32_16x16x32_bf16 v[104:107], v[170:173], v[224:227], v[104:107]
	v_mfma_f32_16x16x32_bf16 v[108:111], v[128:131], v[224:227], v[108:111]
	v_mfma_f32_16x16x32_bf16 v[92:95], v[128:131], v[232:235], v[92:95]
	v_mfma_f32_16x16x32_bf16 v[88:91], v[170:173], v[232:235], v[88:91]
	v_mfma_f32_16x16x32_bf16 v[72:75], v[170:173], v[240:243], v[72:75]
	v_mfma_f32_16x16x32_bf16 v[76:79], v[128:131], v[240:243], v[76:79]
	v_mfma_f32_16x16x32_bf16 v[124:127], v[166:169], v[220:223], v[124:127]
	v_mfma_f32_16x16x32_bf16 v[120:123], v[174:177], v[220:223], v[120:123]
	v_mfma_f32_16x16x32_bf16 v[104:107], v[174:177], v[228:231], v[104:107]
	v_mfma_f32_16x16x32_bf16 v[108:111], v[166:169], v[228:231], v[108:111]
	v_mfma_f32_16x16x32_bf16 v[92:95], v[166:169], v[236:239], v[92:95]
	v_mfma_f32_16x16x32_bf16 v[88:91], v[174:177], v[236:239], v[88:91]
	v_mfma_f32_16x16x32_bf16 v[72:75], v[174:177], v[244:247], v[72:75]
	v_mfma_f32_16x16x32_bf16 v[76:79], v[166:169], v[244:247], v[76:79]
	s_setprio 0
	s_setprio 1
	v_mfma_f32_16x16x32_bf16 v[116:119], v[178:181], v[216:219], v[116:119]
	v_mfma_f32_16x16x32_bf16 v[112:115], v[208:211], v[216:219], v[112:115]
	v_mfma_f32_16x16x32_bf16 v[96:99], v[208:211], v[224:227], v[96:99]
	v_mfma_f32_16x16x32_bf16 v[100:103], v[178:181], v[224:227], v[100:103]
	v_mfma_f32_16x16x32_bf16 v[84:87], v[178:181], v[232:235], v[84:87]
	v_mfma_f32_16x16x32_bf16 v[80:83], v[208:211], v[232:235], v[80:83]
	v_mfma_f32_16x16x32_bf16 v[64:67], v[208:211], v[240:243], v[64:67]
	v_mfma_f32_16x16x32_bf16 v[68:71], v[178:181], v[240:243], v[68:71]
	v_mfma_f32_16x16x32_bf16 v[116:119], v[204:207], v[220:223], v[116:119]
	v_mfma_f32_16x16x32_bf16 v[112:115], v[212:215], v[220:223], v[112:115]
	v_mfma_f32_16x16x32_bf16 v[96:99], v[212:215], v[228:231], v[96:99]
	v_mfma_f32_16x16x32_bf16 v[100:103], v[204:207], v[228:231], v[100:103]
	v_mfma_f32_16x16x32_bf16 v[84:87], v[204:207], v[236:239], v[84:87]
	v_mfma_f32_16x16x32_bf16 v[80:83], v[212:215], v[236:239], v[80:83]
	v_mfma_f32_16x16x32_bf16 v[64:67], v[212:215], v[244:247], v[64:67]
	v_mfma_f32_16x16x32_bf16 v[68:71], v[204:207], v[244:247], v[68:71]
	s_setprio 0
	s_barrier
	s_add_i32 s38, s40, s86
	v_lshl_add_u64 v[248:249], s[42:43], 0, v[134:135]
	s_mov_b32 m0, s38
	ds_read_b128 v[216:219], v155 offset:16384
	ds_read_b128 v[220:223], v155 offset:17408
	ds_read_b128 v[224:227], v155 offset:18432
	ds_read_b128 v[228:231], v155 offset:19456
	ds_read_b128 v[232:235], v155 offset:20480
	ds_read_b128 v[236:239], v155 offset:21504
	ds_read_b128 v[240:243], v155 offset:22528
	ds_read_b128 v[244:247], v155 offset:23552
	global_load_lds_dwordx4 v[248:249], off
	s_add_i32 m0, s38, 0x2000
	s_add_u32 s44, s42, 0x40000
	v_lshl_add_u64 v[250:251], s[42:43], 0, v[138:139]
	s_addc_u32 s45, s43, 0
	s_add_i32 s37, s37, s86
	global_load_lds_dwordx4 v[250:251], off
	v_lshl_add_u64 v[252:253], s[44:45], 0, v[134:135]
	s_mov_b32 m0, s37
	v_lshl_add_u64 v[190:191], s[54:55], 0, v[136:137]
	global_load_lds_dwordx4 v[252:253], off
	v_lshl_add_u64 v[252:253], s[44:45], 0, v[138:139]
	s_add_i32 m0, s37, 0x2000
	s_nop 0
	global_load_lds_dwordx4 v[252:253], off
	v_lshl_add_u64 v[252:253], s[54:55], 0, v[132:133]
	s_mov_b32 m0, s87
	s_nop 0
	global_load_lds_dwordx4 v[252:253], off
	s_mov_b32 m0, s76
	s_nop 0
	global_load_lds_dwordx4 v[190:191], off
	s_waitcnt vmcnt(8)
	s_waitcnt lgkmcnt(0)
	s_barrier
	s_setprio 1
	s_waitcnt lgkmcnt(0)
	v_mfma_f32_16x16x32_bf16 v[60:63], v[128:131], v[216:219], v[60:63]
	v_mfma_f32_16x16x32_bf16 v[56:59], v[170:173], v[216:219], v[56:59]
	v_mfma_f32_16x16x32_bf16 v[40:43], v[170:173], v[224:227], v[40:43]
	v_mfma_f32_16x16x32_bf16 v[44:47], v[128:131], v[224:227], v[44:47]
	v_mfma_f32_16x16x32_bf16 v[28:31], v[128:131], v[232:235], v[28:31]
	v_mfma_f32_16x16x32_bf16 v[24:27], v[170:173], v[232:235], v[24:27]
	v_mfma_f32_16x16x32_bf16 v[8:11], v[170:173], v[240:243], v[8:11]
	v_mfma_f32_16x16x32_bf16 v[12:15], v[128:131], v[240:243], v[12:15]
	v_mfma_f32_16x16x32_bf16 v[60:63], v[166:169], v[220:223], v[60:63]
	v_mfma_f32_16x16x32_bf16 v[56:59], v[174:177], v[220:223], v[56:59]
	v_mfma_f32_16x16x32_bf16 v[40:43], v[174:177], v[228:231], v[40:43]
	v_mfma_f32_16x16x32_bf16 v[44:47], v[166:169], v[228:231], v[44:47]
	v_mfma_f32_16x16x32_bf16 v[28:31], v[166:169], v[236:239], v[28:31]
	v_mfma_f32_16x16x32_bf16 v[24:27], v[174:177], v[236:239], v[24:27]
	v_mfma_f32_16x16x32_bf16 v[8:11], v[174:177], v[244:247], v[8:11]
	v_mfma_f32_16x16x32_bf16 v[12:15], v[166:169], v[244:247], v[12:15]
	s_setprio 0
	s_setprio 1
	v_mfma_f32_16x16x32_bf16 v[52:55], v[178:181], v[216:219], v[52:55]
	v_mfma_f32_16x16x32_bf16 v[48:51], v[208:211], v[216:219], v[48:51]
	v_mfma_f32_16x16x32_bf16 v[32:35], v[208:211], v[224:227], v[32:35]
	v_mfma_f32_16x16x32_bf16 v[36:39], v[178:181], v[224:227], v[36:39]
	v_mfma_f32_16x16x32_bf16 v[20:23], v[178:181], v[232:235], v[20:23]
	v_mfma_f32_16x16x32_bf16 v[16:19], v[208:211], v[232:235], v[16:19]
	v_mfma_f32_16x16x32_bf16 v[0:3], v[208:211], v[240:243], v[0:3]
	v_mfma_f32_16x16x32_bf16 v[4:7], v[178:181], v[240:243], v[4:7]
	v_mfma_f32_16x16x32_bf16 v[52:55], v[204:207], v[220:223], v[52:55]
	v_mfma_f32_16x16x32_bf16 v[48:51], v[212:215], v[220:223], v[48:51]
	v_mfma_f32_16x16x32_bf16 v[32:35], v[212:215], v[228:231], v[32:35]
	v_mfma_f32_16x16x32_bf16 v[36:39], v[204:207], v[228:231], v[36:39]
	v_mfma_f32_16x16x32_bf16 v[20:23], v[204:207], v[236:239], v[20:23]
	v_mfma_f32_16x16x32_bf16 v[16:19], v[212:215], v[236:239], v[16:19]
	v_mfma_f32_16x16x32_bf16 v[0:3], v[212:215], v[244:247], v[0:3]
	v_mfma_f32_16x16x32_bf16 v[4:7], v[204:207], v[244:247], v[4:7]
	s_setprio 0
	s_barrier
	s_add_i32 s37, 0, 0x18000
	v_add_u32_e32 v144, s37, v141
	s_add_i32 s38, 0, 0x1c000
	ds_read_b128 v[128:131], v144
	ds_read_b128 v[166:169], v144 offset:1024
	ds_read_b128 v[170:173], v144 offset:2048
	ds_read_b128 v[174:177], v144 offset:3072
	v_add_u32_e32 v144, s38, v141
	ds_read_b128 v[178:181], v144
	ds_read_b128 v[204:207], v144 offset:1024
	ds_read_b128 v[208:211], v144 offset:2048
	ds_read_b128 v[212:215], v144 offset:3072
	s_add_u32 s44, s54, 0x40000
	s_addc_u32 s45, s55, 0
	s_mov_b32 m0, s77
	v_lshl_add_u64 v[192:193], s[44:45], 0, v[132:133]
	ds_read_b128 v[216:219], v155 offset:32768
	ds_read_b128 v[220:223], v155 offset:33792
	ds_read_b128 v[224:227], v155 offset:34816
	ds_read_b128 v[228:231], v155 offset:35840
	ds_read_b128 v[232:235], v155 offset:36864
	ds_read_b128 v[236:239], v155 offset:37888
	ds_read_b128 v[240:243], v155 offset:38912
	ds_read_b128 v[244:247], v155 offset:39936
	global_load_lds_dwordx4 v[192:193], off
	v_lshl_add_u64 v[192:193], s[44:45], 0, v[136:137]
	s_mov_b32 m0, s74
	s_nop 0
	global_load_lds_dwordx4 v[192:193], off
	s_waitcnt vmcnt(8)
	s_waitcnt lgkmcnt(0)
	s_barrier
	s_setprio 1
	s_waitcnt lgkmcnt(0)
	v_mfma_f32_16x16x32_bf16 v[124:127], v[128:131], v[216:219], v[124:127]
	v_mfma_f32_16x16x32_bf16 v[120:123], v[170:173], v[216:219], v[120:123]
	v_mfma_f32_16x16x32_bf16 v[104:107], v[170:173], v[224:227], v[104:107]
	v_mfma_f32_16x16x32_bf16 v[108:111], v[128:131], v[224:227], v[108:111]
	v_mfma_f32_16x16x32_bf16 v[92:95], v[128:131], v[232:235], v[92:95]
	v_mfma_f32_16x16x32_bf16 v[88:91], v[170:173], v[232:235], v[88:91]
	v_mfma_f32_16x16x32_bf16 v[72:75], v[170:173], v[240:243], v[72:75]
	v_mfma_f32_16x16x32_bf16 v[76:79], v[128:131], v[240:243], v[76:79]
	v_mfma_f32_16x16x32_bf16 v[124:127], v[166:169], v[220:223], v[124:127]
	v_mfma_f32_16x16x32_bf16 v[120:123], v[174:177], v[220:223], v[120:123]
	v_mfma_f32_16x16x32_bf16 v[104:107], v[174:177], v[228:231], v[104:107]
	v_mfma_f32_16x16x32_bf16 v[108:111], v[166:169], v[228:231], v[108:111]
	v_mfma_f32_16x16x32_bf16 v[92:95], v[166:169], v[236:239], v[92:95]
	v_mfma_f32_16x16x32_bf16 v[88:91], v[174:177], v[236:239], v[88:91]
	v_mfma_f32_16x16x32_bf16 v[72:75], v[174:177], v[244:247], v[72:75]
	v_mfma_f32_16x16x32_bf16 v[76:79], v[166:169], v[244:247], v[76:79]
	s_setprio 0
	s_setprio 1
	v_mfma_f32_16x16x32_bf16 v[116:119], v[178:181], v[216:219], v[116:119]
	v_mfma_f32_16x16x32_bf16 v[112:115], v[208:211], v[216:219], v[112:115]
	v_mfma_f32_16x16x32_bf16 v[96:99], v[208:211], v[224:227], v[96:99]
	v_mfma_f32_16x16x32_bf16 v[100:103], v[178:181], v[224:227], v[100:103]
	v_mfma_f32_16x16x32_bf16 v[84:87], v[178:181], v[232:235], v[84:87]
	v_mfma_f32_16x16x32_bf16 v[80:83], v[208:211], v[232:235], v[80:83]
	v_mfma_f32_16x16x32_bf16 v[64:67], v[208:211], v[240:243], v[64:67]
	v_mfma_f32_16x16x32_bf16 v[68:71], v[178:181], v[240:243], v[68:71]
	v_mfma_f32_16x16x32_bf16 v[116:119], v[204:207], v[220:223], v[116:119]
	v_mfma_f32_16x16x32_bf16 v[112:115], v[212:215], v[220:223], v[112:115]
	v_mfma_f32_16x16x32_bf16 v[96:99], v[212:215], v[228:231], v[96:99]
	v_mfma_f32_16x16x32_bf16 v[100:103], v[204:207], v[228:231], v[100:103]
	v_mfma_f32_16x16x32_bf16 v[84:87], v[204:207], v[236:239], v[84:87]
	v_mfma_f32_16x16x32_bf16 v[80:83], v[212:215], v[236:239], v[80:83]
	v_mfma_f32_16x16x32_bf16 v[64:67], v[212:215], v[244:247], v[64:67]
	v_mfma_f32_16x16x32_bf16 v[68:71], v[204:207], v[244:247], v[68:71]
	s_setprio 0
	s_barrier
	s_add_i32 s37, s37, s86
	v_lshl_add_u64 v[192:193], v[248:249], 0, s[48:49]
	s_mov_b32 m0, s37
	ds_read_b128 v[216:219], v155 offset:49152
	ds_read_b128 v[220:223], v155 offset:50176
	ds_read_b128 v[224:227], v155 offset:51200
	ds_read_b128 v[228:231], v155 offset:52224
	ds_read_b128 v[232:235], v155 offset:53248
	ds_read_b128 v[236:239], v155 offset:54272
	ds_read_b128 v[240:243], v155 offset:55296
	ds_read_b128 v[244:247], v155 offset:56320
	global_load_lds_dwordx4 v[192:193], off
	s_add_i32 m0, s37, 0x2000
	s_add_u32 s42, s42, 0x40080
	v_lshl_add_u64 v[192:193], v[250:251], 0, s[48:49]
	s_addc_u32 s43, s43, 0
	s_add_i32 s37, s38, s86
	global_load_lds_dwordx4 v[192:193], off
	v_lshl_add_u64 v[192:193], s[42:43], 0, v[134:135]
	s_mov_b32 m0, s37
	v_lshl_add_u64 v[190:191], v[190:191], 0, s[48:49]
	global_load_lds_dwordx4 v[192:193], off
	v_lshl_add_u64 v[192:193], s[42:43], 0, v[138:139]
	s_add_i32 m0, s37, 0x2000
	s_nop 0
	global_load_lds_dwordx4 v[192:193], off
	v_lshl_add_u64 v[192:193], v[252:253], 0, s[48:49]
	s_mov_b32 m0, s82
	s_nop 0
	global_load_lds_dwordx4 v[192:193], off
	s_mov_b32 m0, s83
	s_nop 0
	global_load_lds_dwordx4 v[190:191], off
	s_waitcnt vmcnt(8)
	s_waitcnt lgkmcnt(0)
	s_barrier
	s_setprio 1
	s_waitcnt lgkmcnt(0)
	v_mfma_f32_16x16x32_bf16 v[60:63], v[128:131], v[216:219], v[60:63]
	v_mfma_f32_16x16x32_bf16 v[56:59], v[170:173], v[216:219], v[56:59]
	v_mfma_f32_16x16x32_bf16 v[40:43], v[170:173], v[224:227], v[40:43]
	v_mfma_f32_16x16x32_bf16 v[44:47], v[128:131], v[224:227], v[44:47]
	v_mfma_f32_16x16x32_bf16 v[28:31], v[128:131], v[232:235], v[28:31]
	v_mfma_f32_16x16x32_bf16 v[24:27], v[170:173], v[232:235], v[24:27]
	v_mfma_f32_16x16x32_bf16 v[8:11], v[170:173], v[240:243], v[8:11]
	v_mfma_f32_16x16x32_bf16 v[12:15], v[128:131], v[240:243], v[12:15]
	v_mfma_f32_16x16x32_bf16 v[60:63], v[166:169], v[220:223], v[60:63]
	v_mfma_f32_16x16x32_bf16 v[56:59], v[174:177], v[220:223], v[56:59]
	v_mfma_f32_16x16x32_bf16 v[40:43], v[174:177], v[228:231], v[40:43]
	v_mfma_f32_16x16x32_bf16 v[44:47], v[166:169], v[228:231], v[44:47]
	v_mfma_f32_16x16x32_bf16 v[28:31], v[166:169], v[236:239], v[28:31]
	v_mfma_f32_16x16x32_bf16 v[24:27], v[174:177], v[236:239], v[24:27]
	v_mfma_f32_16x16x32_bf16 v[8:11], v[174:177], v[244:247], v[8:11]
	v_mfma_f32_16x16x32_bf16 v[12:15], v[166:169], v[244:247], v[12:15]
	s_setprio 0
	s_setprio 1
	v_mfma_f32_16x16x32_bf16 v[52:55], v[178:181], v[216:219], v[52:55]
	v_mfma_f32_16x16x32_bf16 v[48:51], v[208:211], v[216:219], v[48:51]
	v_mfma_f32_16x16x32_bf16 v[32:35], v[208:211], v[224:227], v[32:35]
	v_mfma_f32_16x16x32_bf16 v[36:39], v[178:181], v[224:227], v[36:39]
	v_mfma_f32_16x16x32_bf16 v[20:23], v[178:181], v[232:235], v[20:23]
	v_mfma_f32_16x16x32_bf16 v[16:19], v[208:211], v[232:235], v[16:19]
	v_mfma_f32_16x16x32_bf16 v[0:3], v[208:211], v[240:243], v[0:3]
	v_mfma_f32_16x16x32_bf16 v[4:7], v[178:181], v[240:243], v[4:7]
	v_mfma_f32_16x16x32_bf16 v[52:55], v[204:207], v[220:223], v[52:55]
	v_mfma_f32_16x16x32_bf16 v[48:51], v[212:215], v[220:223], v[48:51]
	v_mfma_f32_16x16x32_bf16 v[32:35], v[212:215], v[228:231], v[32:35]
	v_mfma_f32_16x16x32_bf16 v[36:39], v[204:207], v[228:231], v[36:39]
	v_mfma_f32_16x16x32_bf16 v[20:23], v[204:207], v[236:239], v[20:23]
	v_mfma_f32_16x16x32_bf16 v[16:19], v[212:215], v[236:239], v[16:19]
	v_mfma_f32_16x16x32_bf16 v[0:3], v[212:215], v[244:247], v[0:3]
	v_mfma_f32_16x16x32_bf16 v[4:7], v[204:207], v[244:247], v[4:7]
	s_setprio 0
	s_barrier
	s_add_i32 s36, s36, 2
	s_add_u32 s4, s4, 0x100
	s_addc_u32 s5, s5, 0
	s_add_u32 s30, s30, 0x100
	s_addc_u32 s31, s31, 0
	s_cmp_gt_u32 s36, 13
	s_cbranch_scc0 .LBB0_594
	s_and_b64 vcc, exec, s[20:21]
	s_cbranch_vccz .LBB0_597
	s_barrier

.LBB0_979:
	s_add_u32 s12, s33, s10
	s_addc_u32 s13, s36, s11
	s_add_u32 s12, s12, 0x200100
	s_addc_u32 s13, s13, 0
	s_add_u32 s41, s37, s10
	s_addc_u32 s42, s38, s11
	s_add_i32 s43, 0, 0x10000
	s_cmpk_eq_i32 s10, 0xf00
	s_cselect_b32 s15, s9, s13
	s_cselect_b32 s14, s8, s12
	v_add_u32_e32 v142, s43, v140
	s_cselect_b32 s13, s7, s42
	s_cselect_b32 s12, s6, s41
	s_add_i32 s41, 0, 0x14000
	ds_read_b128 v[154:157], v142
	ds_read_b128 v[158:161], v142 offset:1024
	ds_read_b128 v[162:165], v142 offset:2048
	ds_read_b128 v[168:171], v142 offset:3072
	v_add_u32_e32 v142, s41, v140
	ds_read_b128 v[172:175], v142
	ds_read_b128 v[176:179], v142 offset:1024
	ds_read_b128 v[204:207], v142 offset:2048
	ds_read_b128 v[208:211], v142 offset:3072
	v_lshl_add_u64 v[142:143], v[136:137], 0, s[10:11]
	s_add_i32 m0, s23, 0xc000
	ds_read_b128 v[212:215], v141
	ds_read_b128 v[216:219], v141 offset:1024
	ds_read_b128 v[220:223], v141 offset:2048
	ds_read_b128 v[224:227], v141 offset:3072
	ds_read_b128 v[228:231], v141 offset:4096
	ds_read_b128 v[232:235], v141 offset:5120
	ds_read_b128 v[236:239], v141 offset:6144
	ds_read_b128 v[240:243], v141 offset:7168
	global_load_lds_dwordx4 v[142:143], off
	v_lshl_add_u64 v[142:143], v[138:139], 0, s[10:11]
	s_add_i32 m0, s23, 0xe000
	s_nop 0
	global_load_lds_dwordx4 v[142:143], off
	s_waitcnt vmcnt(8)
	s_waitcnt lgkmcnt(0)
	s_barrier
	s_setprio 1
	s_waitcnt lgkmcnt(0)
	v_mfma_f32_16x16x32_bf16 v[124:127], v[154:157], v[212:215], v[124:127]
	v_mfma_f32_16x16x32_bf16 v[120:123], v[162:165], v[212:215], v[120:123]
	v_mfma_f32_16x16x32_bf16 v[104:107], v[162:165], v[220:223], v[104:107]
	v_mfma_f32_16x16x32_bf16 v[112:115], v[154:157], v[220:223], v[112:115]
	v_mfma_f32_16x16x32_bf16 v[96:99], v[154:157], v[228:231], v[96:99]
	v_mfma_f32_16x16x32_bf16 v[88:91], v[162:165], v[228:231], v[88:91]
	v_mfma_f32_16x16x32_bf16 v[72:75], v[162:165], v[236:239], v[72:75]
	v_mfma_f32_16x16x32_bf16 v[80:83], v[154:157], v[236:239], v[80:83]
	v_mfma_f32_16x16x32_bf16 v[124:127], v[158:161], v[216:219], v[124:127]
	v_mfma_f32_16x16x32_bf16 v[120:123], v[168:171], v[216:219], v[120:123]
	v_mfma_f32_16x16x32_bf16 v[104:107], v[168:171], v[224:227], v[104:107]
	v_mfma_f32_16x16x32_bf16 v[112:115], v[158:161], v[224:227], v[112:115]
	v_mfma_f32_16x16x32_bf16 v[96:99], v[158:161], v[232:235], v[96:99]
	v_mfma_f32_16x16x32_bf16 v[88:91], v[168:171], v[232:235], v[88:91]
	v_mfma_f32_16x16x32_bf16 v[72:75], v[168:171], v[240:243], v[72:75]
	v_mfma_f32_16x16x32_bf16 v[80:83], v[158:161], v[240:243], v[80:83]
	s_setprio 0
	s_setprio 1
	v_mfma_f32_16x16x32_bf16 v[116:119], v[172:175], v[212:215], v[116:119]
	v_mfma_f32_16x16x32_bf16 v[108:111], v[204:207], v[212:215], v[108:111]
	v_mfma_f32_16x16x32_bf16 v[92:95], v[204:207], v[220:223], v[92:95]
	v_mfma_f32_16x16x32_bf16 v[100:103], v[172:175], v[220:223], v[100:103]
	v_mfma_f32_16x16x32_bf16 v[84:87], v[172:175], v[228:231], v[84:87]
	v_mfma_f32_16x16x32_bf16 v[76:79], v[204:207], v[228:231], v[76:79]
	v_mfma_f32_16x16x32_bf16 v[64:67], v[204:207], v[236:239], v[64:67]
	v_mfma_f32_16x16x32_bf16 v[68:71], v[172:175], v[236:239], v[68:71]
	v_mfma_f32_16x16x32_bf16 v[116:119], v[176:179], v[216:219], v[116:119]
	v_mfma_f32_16x16x32_bf16 v[108:111], v[208:211], v[216:219], v[108:111]
	v_mfma_f32_16x16x32_bf16 v[92:95], v[208:211], v[224:227], v[92:95]
	v_mfma_f32_16x16x32_bf16 v[100:103], v[176:179], v[224:227], v[100:103]
	v_mfma_f32_16x16x32_bf16 v[84:87], v[176:179], v[232:235], v[84:87]
	v_mfma_f32_16x16x32_bf16 v[76:79], v[208:211], v[232:235], v[76:79]
	v_mfma_f32_16x16x32_bf16 v[64:67], v[208:211], v[240:243], v[64:67]
	v_mfma_f32_16x16x32_bf16 v[68:71], v[176:179], v[240:243], v[68:71]
	s_setprio 0
	s_barrier
	s_add_i32 s42, s43, s19
	v_lshl_add_u64 v[142:143], s[12:13], 0, v[144:145]
	s_mov_b32 m0, s42
	ds_read_b128 v[212:215], v141 offset:16384
	ds_read_b128 v[216:219], v141 offset:17408
	ds_read_b128 v[220:223], v141 offset:18432
	ds_read_b128 v[224:227], v141 offset:19456
	ds_read_b128 v[228:231], v141 offset:20480
	ds_read_b128 v[232:235], v141 offset:21504
	ds_read_b128 v[236:239], v141 offset:22528
	ds_read_b128 v[240:243], v141 offset:23552
	global_load_lds_dwordx4 v[142:143], off
	s_add_i32 m0, s42, 0x2000
	s_add_u32 s42, s12, 0x80000
	v_lshl_add_u64 v[180:181], s[12:13], 0, v[130:131]
	s_addc_u32 s43, s13, 0
	s_add_i32 s41, s41, s19
	global_load_lds_dwordx4 v[180:181], off
	v_lshl_add_u64 v[190:191], s[42:43], 0, v[144:145]
	s_mov_b32 m0, s41
	v_lshl_add_u64 v[192:193], s[14:15], 0, v[132:133]
	global_load_lds_dwordx4 v[190:191], off
	v_lshl_add_u64 v[190:191], s[42:43], 0, v[130:131]
	s_add_i32 m0, s41, 0x2000
	s_nop 0
	global_load_lds_dwordx4 v[190:191], off
	v_lshl_add_u64 v[190:191], s[14:15], 0, v[134:135]
	s_mov_b32 m0, s23
	s_nop 0
	global_load_lds_dwordx4 v[190:191], off
	s_mov_b32 m0, s24
	s_nop 0
	global_load_lds_dwordx4 v[192:193], off
	s_waitcnt vmcnt(8)
	s_waitcnt lgkmcnt(0)
	s_barrier
	s_setprio 1
	s_waitcnt lgkmcnt(0)
	v_mfma_f32_16x16x32_bf16 v[60:63], v[154:157], v[212:215], v[60:63]
	v_mfma_f32_16x16x32_bf16 v[56:59], v[162:165], v[212:215], v[56:59]
	v_mfma_f32_16x16x32_bf16 v[44:47], v[162:165], v[220:223], v[44:47]
	v_mfma_f32_16x16x32_bf16 v[52:55], v[154:157], v[220:223], v[52:55]
	v_mfma_f32_16x16x32_bf16 v[36:39], v[154:157], v[228:231], v[36:39]
	v_mfma_f32_16x16x32_bf16 v[28:31], v[162:165], v[228:231], v[28:31]
	v_mfma_f32_16x16x32_bf16 v[12:15], v[162:165], v[236:239], v[12:15]
	v_mfma_f32_16x16x32_bf16 v[20:23], v[154:157], v[236:239], v[20:23]
	v_mfma_f32_16x16x32_bf16 v[60:63], v[158:161], v[216:219], v[60:63]
	v_mfma_f32_16x16x32_bf16 v[56:59], v[168:171], v[216:219], v[56:59]
	v_mfma_f32_16x16x32_bf16 v[44:47], v[168:171], v[224:227], v[44:47]
	v_mfma_f32_16x16x32_bf16 v[52:55], v[158:161], v[224:227], v[52:55]
	v_mfma_f32_16x16x32_bf16 v[36:39], v[158:161], v[232:235], v[36:39]
	v_mfma_f32_16x16x32_bf16 v[28:31], v[168:171], v[232:235], v[28:31]
	v_mfma_f32_16x16x32_bf16 v[12:15], v[168:171], v[240:243], v[12:15]
	v_mfma_f32_16x16x32_bf16 v[20:23], v[158:161], v[240:243], v[20:23]
	s_setprio 0
	s_setprio 1
	v_mfma_f32_16x16x32_bf16 v[48:51], v[172:175], v[212:215], v[48:51]
	v_mfma_f32_16x16x32_bf16 v[40:43], v[204:207], v[212:215], v[40:43]
	v_mfma_f32_16x16x32_bf16 v[24:27], v[204:207], v[220:223], v[24:27]
	v_mfma_f32_16x16x32_bf16 v[32:35], v[172:175], v[220:223], v[32:35]
	v_mfma_f32_16x16x32_bf16 v[16:19], v[172:175], v[228:231], v[16:19]
	v_mfma_f32_16x16x32_bf16 v[8:11], v[204:207], v[228:231], v[8:11]
	v_mfma_f32_16x16x32_bf16 v[0:3], v[204:207], v[236:239], v[0:3]
	v_mfma_f32_16x16x32_bf16 v[4:7], v[172:175], v[236:239], v[4:7]
	v_mfma_f32_16x16x32_bf16 v[48:51], v[176:179], v[216:219], v[48:51]
	v_mfma_f32_16x16x32_bf16 v[40:43], v[208:211], v[216:219], v[40:43]
	v_mfma_f32_16x16x32_bf16 v[24:27], v[208:211], v[224:227], v[24:27]
	v_mfma_f32_16x16x32_bf16 v[32:35], v[176:179], v[224:227], v[32:35]
	v_mfma_f32_16x16x32_bf16 v[16:19], v[176:179], v[232:235], v[16:19]
	v_mfma_f32_16x16x32_bf16 v[8:11], v[208:211], v[232:235], v[8:11]
	v_mfma_f32_16x16x32_bf16 v[0:3], v[208:211], v[240:243], v[0:3]
	v_mfma_f32_16x16x32_bf16 v[4:7], v[176:179], v[240:243], v[4:7]
	s_setprio 0
	s_barrier
	s_add_i32 s41, 0, 0x18000
	v_add_u32_e32 v167, s41, v140
	s_add_i32 s42, 0, 0x1c000
	ds_read_b128 v[154:157], v167
	ds_read_b128 v[158:161], v167 offset:1024
	ds_read_b128 v[162:165], v167 offset:2048
	ds_read_b128 v[168:171], v167 offset:3072
	v_add_u32_e32 v167, s42, v140
	ds_read_b128 v[172:175], v167
	ds_read_b128 v[176:179], v167 offset:1024
	ds_read_b128 v[204:207], v167 offset:2048
	ds_read_b128 v[208:211], v167 offset:3072
	s_add_u32 s14, s14, 0x80000
	s_addc_u32 s15, s15, 0
	s_mov_b32 m0, s25
	v_lshl_add_u64 v[244:245], s[14:15], 0, v[134:135]
	ds_read_b128 v[212:215], v141 offset:32768
	ds_read_b128 v[216:219], v141 offset:33792
	ds_read_b128 v[220:223], v141 offset:34816
	ds_read_b128 v[224:227], v141 offset:35840
	ds_read_b128 v[228:231], v141 offset:36864
	ds_read_b128 v[232:235], v141 offset:37888
	ds_read_b128 v[236:239], v141 offset:38912
	ds_read_b128 v[240:243], v141 offset:39936
	global_load_lds_dwordx4 v[244:245], off
	v_lshl_add_u64 v[244:245], s[14:15], 0, v[132:133]
	s_mov_b32 m0, s26
	s_nop 0
	global_load_lds_dwordx4 v[244:245], off
	s_waitcnt vmcnt(8)
	s_waitcnt lgkmcnt(0)
	s_barrier
	s_setprio 1
	s_waitcnt lgkmcnt(0)
	v_mfma_f32_16x16x32_bf16 v[124:127], v[154:157], v[212:215], v[124:127]
	v_mfma_f32_16x16x32_bf16 v[120:123], v[162:165], v[212:215], v[120:123]
	v_mfma_f32_16x16x32_bf16 v[104:107], v[162:165], v[220:223], v[104:107]
	v_mfma_f32_16x16x32_bf16 v[112:115], v[154:157], v[220:223], v[112:115]
	v_mfma_f32_16x16x32_bf16 v[96:99], v[154:157], v[228:231], v[96:99]
	v_mfma_f32_16x16x32_bf16 v[88:91], v[162:165], v[228:231], v[88:91]
	v_mfma_f32_16x16x32_bf16 v[72:75], v[162:165], v[236:239], v[72:75]
	v_mfma_f32_16x16x32_bf16 v[80:83], v[154:157], v[236:239], v[80:83]
	v_mfma_f32_16x16x32_bf16 v[124:127], v[158:161], v[216:219], v[124:127]
	v_mfma_f32_16x16x32_bf16 v[120:123], v[168:171], v[216:219], v[120:123]
	v_mfma_f32_16x16x32_bf16 v[104:107], v[168:171], v[224:227], v[104:107]
	v_mfma_f32_16x16x32_bf16 v[112:115], v[158:161], v[224:227], v[112:115]
	v_mfma_f32_16x16x32_bf16 v[96:99], v[158:161], v[232:235], v[96:99]
	v_mfma_f32_16x16x32_bf16 v[88:91], v[168:171], v[232:235], v[88:91]
	v_mfma_f32_16x16x32_bf16 v[72:75], v[168:171], v[240:243], v[72:75]
	v_mfma_f32_16x16x32_bf16 v[80:83], v[158:161], v[240:243], v[80:83]
	s_setprio 0
	s_setprio 1
	v_mfma_f32_16x16x32_bf16 v[116:119], v[172:175], v[212:215], v[116:119]
	v_mfma_f32_16x16x32_bf16 v[108:111], v[204:207], v[212:215], v[108:111]
	v_mfma_f32_16x16x32_bf16 v[92:95], v[204:207], v[220:223], v[92:95]
	v_mfma_f32_16x16x32_bf16 v[100:103], v[172:175], v[220:223], v[100:103]
	v_mfma_f32_16x16x32_bf16 v[84:87], v[172:175], v[228:231], v[84:87]
	v_mfma_f32_16x16x32_bf16 v[76:79], v[204:207], v[228:231], v[76:79]
	v_mfma_f32_16x16x32_bf16 v[64:67], v[204:207], v[236:239], v[64:67]
	v_mfma_f32_16x16x32_bf16 v[68:71], v[172:175], v[236:239], v[68:71]
	v_mfma_f32_16x16x32_bf16 v[116:119], v[176:179], v[216:219], v[116:119]
	v_mfma_f32_16x16x32_bf16 v[108:111], v[208:211], v[216:219], v[108:111]
	v_mfma_f32_16x16x32_bf16 v[92:95], v[208:211], v[224:227], v[92:95]
	v_mfma_f32_16x16x32_bf16 v[100:103], v[176:179], v[224:227], v[100:103]
	v_mfma_f32_16x16x32_bf16 v[84:87], v[176:179], v[232:235], v[84:87]
	v_mfma_f32_16x16x32_bf16 v[76:79], v[208:211], v[232:235], v[76:79]
	v_mfma_f32_16x16x32_bf16 v[64:67], v[208:211], v[240:243], v[64:67]
	v_mfma_f32_16x16x32_bf16 v[68:71], v[176:179], v[240:243], v[68:71]
	s_setprio 0
	s_barrier
	s_add_i32 s14, s41, s19
	v_lshl_add_u64 v[142:143], v[142:143], 0, s[48:49]
	s_mov_b32 m0, s14
	ds_read_b128 v[212:215], v141 offset:49152
	ds_read_b128 v[216:219], v141 offset:50176
	ds_read_b128 v[220:223], v141 offset:51200
	ds_read_b128 v[224:227], v141 offset:52224
	ds_read_b128 v[228:231], v141 offset:53248
	ds_read_b128 v[232:235], v141 offset:54272
	ds_read_b128 v[236:239], v141 offset:55296
	ds_read_b128 v[240:243], v141 offset:56320
	global_load_lds_dwordx4 v[142:143], off
	s_add_i32 m0, s14, 0x2000
	s_add_u32 s12, s12, 0x80080
	v_lshl_add_u64 v[142:143], v[180:181], 0, s[48:49]
	s_addc_u32 s13, s13, 0
	s_add_i32 s14, s42, s19
	global_load_lds_dwordx4 v[142:143], off
	v_lshl_add_u64 v[142:143], s[12:13], 0, v[144:145]
	s_mov_b32 m0, s14
	s_nop 0
	global_load_lds_dwordx4 v[142:143], off
	v_lshl_add_u64 v[142:143], s[12:13], 0, v[130:131]
	s_add_i32 m0, s14, 0x2000
	s_nop 0
	global_load_lds_dwordx4 v[142:143], off
	v_lshl_add_u64 v[142:143], v[190:191], 0, s[48:49]
	s_mov_b32 m0, s30
	s_nop 0
	global_load_lds_dwordx4 v[142:143], off
	v_lshl_add_u64 v[142:143], v[192:193], 0, s[48:49]
	s_mov_b32 m0, s31
	s_nop 0
	global_load_lds_dwordx4 v[142:143], off
	s_waitcnt vmcnt(8)
	s_waitcnt lgkmcnt(0)
	s_barrier
	s_setprio 1
	s_waitcnt lgkmcnt(0)
	v_mfma_f32_16x16x32_bf16 v[60:63], v[154:157], v[212:215], v[60:63]
	v_mfma_f32_16x16x32_bf16 v[56:59], v[162:165], v[212:215], v[56:59]
	v_mfma_f32_16x16x32_bf16 v[44:47], v[162:165], v[220:223], v[44:47]
	v_mfma_f32_16x16x32_bf16 v[52:55], v[154:157], v[220:223], v[52:55]
	v_mfma_f32_16x16x32_bf16 v[36:39], v[154:157], v[228:231], v[36:39]
	v_mfma_f32_16x16x32_bf16 v[28:31], v[162:165], v[228:231], v[28:31]
	v_mfma_f32_16x16x32_bf16 v[12:15], v[162:165], v[236:239], v[12:15]
	v_mfma_f32_16x16x32_bf16 v[20:23], v[154:157], v[236:239], v[20:23]
	v_mfma_f32_16x16x32_bf16 v[60:63], v[158:161], v[216:219], v[60:63]
	v_mfma_f32_16x16x32_bf16 v[56:59], v[168:171], v[216:219], v[56:59]
	v_mfma_f32_16x16x32_bf16 v[44:47], v[168:171], v[224:227], v[44:47]
	v_mfma_f32_16x16x32_bf16 v[52:55], v[158:161], v[224:227], v[52:55]
	v_mfma_f32_16x16x32_bf16 v[36:39], v[158:161], v[232:235], v[36:39]
	v_mfma_f32_16x16x32_bf16 v[28:31], v[168:171], v[232:235], v[28:31]
	v_mfma_f32_16x16x32_bf16 v[12:15], v[168:171], v[240:243], v[12:15]
	v_mfma_f32_16x16x32_bf16 v[20:23], v[158:161], v[240:243], v[20:23]
	s_setprio 0
	s_setprio 1
	v_mfma_f32_16x16x32_bf16 v[48:51], v[172:175], v[212:215], v[48:51]
	v_mfma_f32_16x16x32_bf16 v[40:43], v[204:207], v[212:215], v[40:43]
	v_mfma_f32_16x16x32_bf16 v[24:27], v[204:207], v[220:223], v[24:27]
	v_mfma_f32_16x16x32_bf16 v[32:35], v[172:175], v[220:223], v[32:35]
	v_mfma_f32_16x16x32_bf16 v[16:19], v[172:175], v[228:231], v[16:19]
	v_mfma_f32_16x16x32_bf16 v[8:11], v[204:207], v[228:231], v[8:11]
	v_mfma_f32_16x16x32_bf16 v[0:3], v[204:207], v[236:239], v[0:3]
	v_mfma_f32_16x16x32_bf16 v[4:7], v[172:175], v[236:239], v[4:7]
	v_mfma_f32_16x16x32_bf16 v[48:51], v[176:179], v[216:219], v[48:51]
	v_mfma_f32_16x16x32_bf16 v[40:43], v[208:211], v[216:219], v[40:43]
	v_mfma_f32_16x16x32_bf16 v[24:27], v[208:211], v[224:227], v[24:27]
	v_mfma_f32_16x16x32_bf16 v[32:35], v[176:179], v[224:227], v[32:35]
	v_mfma_f32_16x16x32_bf16 v[16:19], v[176:179], v[232:235], v[16:19]
	v_mfma_f32_16x16x32_bf16 v[8:11], v[208:211], v[232:235], v[8:11]
	v_mfma_f32_16x16x32_bf16 v[0:3], v[208:211], v[240:243], v[0:3]
	v_mfma_f32_16x16x32_bf16 v[4:7], v[176:179], v[240:243], v[4:7]
	s_setprio 0
	s_barrier
	s_add_i32 s40, s40, 2
	s_add_u32 s10, s10, 0x100
	s_addc_u32 s11, s11, 0
	s_cmp_gt_u32 s40, 29
	s_cbranch_scc0 .LBB0_979
	s_cmpk_lt_u32 s18, 0x100
	s_cbranch_scc0 .LBB0_982
	s_barrier

.LBB0_987:
	s_add_u32 s14, s12, 0x600100
	s_addc_u32 s15, s13, 0
	s_add_u32 s40, s12, s33
	s_addc_u32 s41, s13, s36
	s_add_i32 s42, 0, 0x10000
	s_cmp_eq_u32 s37, 4
	s_cselect_b32 s19, s9, s15
	s_cselect_b32 s18, s8, s14
	v_add_u32_e32 v142, s42, v140
	s_cselect_b32 s15, s11, s41
	s_cselect_b32 s14, s10, s40
	s_add_i32 s43, 0, 0x14000
	ds_read_b128 v[154:157], v142
	ds_read_b128 v[158:161], v142 offset:1024
	ds_read_b128 v[162:165], v142 offset:2048
	ds_read_b128 v[168:171], v142 offset:3072
	v_add_u32_e32 v142, s43, v140
	ds_read_b128 v[172:175], v142
	ds_read_b128 v[176:179], v142 offset:1024
	ds_read_b128 v[204:207], v142 offset:2048
	ds_read_b128 v[208:211], v142 offset:3072
	v_lshl_add_u64 v[142:143], s[12:13], 0, v[136:137]
	s_add_i32 m0, s23, 0xc000
	ds_read_b128 v[212:215], v141
	ds_read_b128 v[216:219], v141 offset:1024
	ds_read_b128 v[220:223], v141 offset:2048
	ds_read_b128 v[224:227], v141 offset:3072
	ds_read_b128 v[228:231], v141 offset:4096
	ds_read_b128 v[232:235], v141 offset:5120
	ds_read_b128 v[236:239], v141 offset:6144
	ds_read_b128 v[240:243], v141 offset:7168
	global_load_lds_dwordx4 v[142:143], off
	v_lshl_add_u64 v[142:143], s[12:13], 0, v[138:139]
	s_add_i32 m0, s23, 0xe000
	s_nop 0
	global_load_lds_dwordx4 v[142:143], off
	s_waitcnt vmcnt(8)
	s_waitcnt lgkmcnt(0)
	s_barrier
	s_setprio 1
	s_waitcnt lgkmcnt(0)
	v_mfma_f32_16x16x32_bf16 v[124:127], v[154:157], v[212:215], v[124:127]
	v_mfma_f32_16x16x32_bf16 v[120:123], v[162:165], v[212:215], v[120:123]
	v_mfma_f32_16x16x32_bf16 v[104:107], v[162:165], v[220:223], v[104:107]
	v_mfma_f32_16x16x32_bf16 v[112:115], v[154:157], v[220:223], v[112:115]
	v_mfma_f32_16x16x32_bf16 v[96:99], v[154:157], v[228:231], v[96:99]
	v_mfma_f32_16x16x32_bf16 v[88:91], v[162:165], v[228:231], v[88:91]
	v_mfma_f32_16x16x32_bf16 v[72:75], v[162:165], v[236:239], v[72:75]
	v_mfma_f32_16x16x32_bf16 v[80:83], v[154:157], v[236:239], v[80:83]
	v_mfma_f32_16x16x32_bf16 v[124:127], v[158:161], v[216:219], v[124:127]
	v_mfma_f32_16x16x32_bf16 v[120:123], v[168:171], v[216:219], v[120:123]
	v_mfma_f32_16x16x32_bf16 v[104:107], v[168:171], v[224:227], v[104:107]
	v_mfma_f32_16x16x32_bf16 v[112:115], v[158:161], v[224:227], v[112:115]
	v_mfma_f32_16x16x32_bf16 v[96:99], v[158:161], v[232:235], v[96:99]
	v_mfma_f32_16x16x32_bf16 v[88:91], v[168:171], v[232:235], v[88:91]
	v_mfma_f32_16x16x32_bf16 v[72:75], v[168:171], v[240:243], v[72:75]
	v_mfma_f32_16x16x32_bf16 v[80:83], v[158:161], v[240:243], v[80:83]
	s_setprio 0
	s_setprio 1
	v_mfma_f32_16x16x32_bf16 v[116:119], v[172:175], v[212:215], v[116:119]
	v_mfma_f32_16x16x32_bf16 v[108:111], v[204:207], v[212:215], v[108:111]
	v_mfma_f32_16x16x32_bf16 v[92:95], v[204:207], v[220:223], v[92:95]
	v_mfma_f32_16x16x32_bf16 v[100:103], v[172:175], v[220:223], v[100:103]
	v_mfma_f32_16x16x32_bf16 v[84:87], v[172:175], v[228:231], v[84:87]
	v_mfma_f32_16x16x32_bf16 v[76:79], v[204:207], v[228:231], v[76:79]
	v_mfma_f32_16x16x32_bf16 v[64:67], v[204:207], v[236:239], v[64:67]
	v_mfma_f32_16x16x32_bf16 v[68:71], v[172:175], v[236:239], v[68:71]
	v_mfma_f32_16x16x32_bf16 v[116:119], v[176:179], v[216:219], v[116:119]
	v_mfma_f32_16x16x32_bf16 v[108:111], v[208:211], v[216:219], v[108:111]
	v_mfma_f32_16x16x32_bf16 v[92:95], v[208:211], v[224:227], v[92:95]
	v_mfma_f32_16x16x32_bf16 v[100:103], v[176:179], v[224:227], v[100:103]
	v_mfma_f32_16x16x32_bf16 v[84:87], v[176:179], v[232:235], v[84:87]
	v_mfma_f32_16x16x32_bf16 v[76:79], v[208:211], v[232:235], v[76:79]
	v_mfma_f32_16x16x32_bf16 v[64:67], v[208:211], v[240:243], v[64:67]
	v_mfma_f32_16x16x32_bf16 v[68:71], v[176:179], v[240:243], v[68:71]
	s_setprio 0
	s_barrier
	s_add_i32 s40, s42, s22
	v_lshl_add_u64 v[142:143], s[14:15], 0, v[144:145]
	s_mov_b32 m0, s40
	ds_read_b128 v[212:215], v141 offset:16384
	ds_read_b128 v[216:219], v141 offset:17408
	ds_read_b128 v[220:223], v141 offset:18432
	ds_read_b128 v[224:227], v141 offset:19456
	ds_read_b128 v[228:231], v141 offset:20480
	ds_read_b128 v[232:235], v141 offset:21504
	ds_read_b128 v[236:239], v141 offset:22528
	ds_read_b128 v[240:243], v141 offset:23552
	global_load_lds_dwordx4 v[142:143], off
	s_add_i32 m0, s40, 0x2000
	s_add_u32 s40, s14, 0x20000
	v_lshl_add_u64 v[180:181], s[14:15], 0, v[130:131]
	s_addc_u32 s41, s15, 0
	s_add_i32 s42, s43, s22
	global_load_lds_dwordx4 v[180:181], off
	v_lshl_add_u64 v[190:191], s[40:41], 0, v[144:145]
	s_mov_b32 m0, s42
	v_lshl_add_u64 v[192:193], s[18:19], 0, v[132:133]
	global_load_lds_dwordx4 v[190:191], off
	v_lshl_add_u64 v[190:191], s[40:41], 0, v[130:131]
	s_add_i32 m0, s42, 0x2000
	s_nop 0
	global_load_lds_dwordx4 v[190:191], off
	v_lshl_add_u64 v[190:191], s[18:19], 0, v[134:135]
	s_mov_b32 m0, s23
	s_nop 0
	global_load_lds_dwordx4 v[190:191], off
	s_mov_b32 m0, s24
	s_nop 0
	global_load_lds_dwordx4 v[192:193], off
	s_waitcnt vmcnt(8)
	s_waitcnt lgkmcnt(0)
	s_barrier
	s_setprio 1
	s_waitcnt lgkmcnt(0)
	v_mfma_f32_16x16x32_bf16 v[60:63], v[154:157], v[212:215], v[60:63]
	v_mfma_f32_16x16x32_bf16 v[56:59], v[162:165], v[212:215], v[56:59]
	v_mfma_f32_16x16x32_bf16 v[44:47], v[162:165], v[220:223], v[44:47]
	v_mfma_f32_16x16x32_bf16 v[52:55], v[154:157], v[220:223], v[52:55]
	v_mfma_f32_16x16x32_bf16 v[36:39], v[154:157], v[228:231], v[36:39]
	v_mfma_f32_16x16x32_bf16 v[28:31], v[162:165], v[228:231], v[28:31]
	v_mfma_f32_16x16x32_bf16 v[12:15], v[162:165], v[236:239], v[12:15]
	v_mfma_f32_16x16x32_bf16 v[20:23], v[154:157], v[236:239], v[20:23]
	v_mfma_f32_16x16x32_bf16 v[60:63], v[158:161], v[216:219], v[60:63]
	v_mfma_f32_16x16x32_bf16 v[56:59], v[168:171], v[216:219], v[56:59]
	v_mfma_f32_16x16x32_bf16 v[44:47], v[168:171], v[224:227], v[44:47]
	v_mfma_f32_16x16x32_bf16 v[52:55], v[158:161], v[224:227], v[52:55]
	v_mfma_f32_16x16x32_bf16 v[36:39], v[158:161], v[232:235], v[36:39]
	v_mfma_f32_16x16x32_bf16 v[28:31], v[168:171], v[232:235], v[28:31]
	v_mfma_f32_16x16x32_bf16 v[12:15], v[168:171], v[240:243], v[12:15]
	v_mfma_f32_16x16x32_bf16 v[20:23], v[158:161], v[240:243], v[20:23]
	s_setprio 0
	s_setprio 1
	v_mfma_f32_16x16x32_bf16 v[48:51], v[172:175], v[212:215], v[48:51]
	v_mfma_f32_16x16x32_bf16 v[40:43], v[204:207], v[212:215], v[40:43]
	v_mfma_f32_16x16x32_bf16 v[24:27], v[204:207], v[220:223], v[24:27]
	v_mfma_f32_16x16x32_bf16 v[32:35], v[172:175], v[220:223], v[32:35]
	v_mfma_f32_16x16x32_bf16 v[16:19], v[172:175], v[228:231], v[16:19]
	v_mfma_f32_16x16x32_bf16 v[8:11], v[204:207], v[228:231], v[8:11]
	v_mfma_f32_16x16x32_bf16 v[0:3], v[204:207], v[236:239], v[0:3]
	v_mfma_f32_16x16x32_bf16 v[4:7], v[172:175], v[236:239], v[4:7]
	v_mfma_f32_16x16x32_bf16 v[48:51], v[176:179], v[216:219], v[48:51]
	v_mfma_f32_16x16x32_bf16 v[40:43], v[208:211], v[216:219], v[40:43]
	v_mfma_f32_16x16x32_bf16 v[24:27], v[208:211], v[224:227], v[24:27]
	v_mfma_f32_16x16x32_bf16 v[32:35], v[176:179], v[224:227], v[32:35]
	v_mfma_f32_16x16x32_bf16 v[16:19], v[176:179], v[232:235], v[16:19]
	v_mfma_f32_16x16x32_bf16 v[8:11], v[208:211], v[232:235], v[8:11]
	v_mfma_f32_16x16x32_bf16 v[0:3], v[208:211], v[240:243], v[0:3]
	v_mfma_f32_16x16x32_bf16 v[4:7], v[176:179], v[240:243], v[4:7]
	s_setprio 0
	s_barrier
	s_add_i32 s40, 0, 0x18000
	v_add_u32_e32 v167, s40, v140
	s_add_i32 s41, 0, 0x1c000
	ds_read_b128 v[154:157], v167
	ds_read_b128 v[158:161], v167 offset:1024
	ds_read_b128 v[162:165], v167 offset:2048
	ds_read_b128 v[168:171], v167 offset:3072
	v_add_u32_e32 v167, s41, v140
	ds_read_b128 v[172:175], v167
	ds_read_b128 v[176:179], v167 offset:1024
	ds_read_b128 v[204:207], v167 offset:2048
	ds_read_b128 v[208:211], v167 offset:3072
	s_add_u32 s18, s18, 0x20000
	s_addc_u32 s19, s19, 0
	s_mov_b32 m0, s25
	v_lshl_add_u64 v[244:245], s[18:19], 0, v[134:135]
	ds_read_b128 v[212:215], v141 offset:32768
	ds_read_b128 v[216:219], v141 offset:33792
	ds_read_b128 v[220:223], v141 offset:34816
	ds_read_b128 v[224:227], v141 offset:35840
	ds_read_b128 v[228:231], v141 offset:36864
	ds_read_b128 v[232:235], v141 offset:37888
	ds_read_b128 v[236:239], v141 offset:38912
	ds_read_b128 v[240:243], v141 offset:39936
	global_load_lds_dwordx4 v[244:245], off
	v_lshl_add_u64 v[244:245], s[18:19], 0, v[132:133]
	s_mov_b32 m0, s26
	s_nop 0
	global_load_lds_dwordx4 v[244:245], off
	s_waitcnt vmcnt(8)
	s_waitcnt lgkmcnt(0)
	s_barrier
	s_setprio 1
	s_waitcnt lgkmcnt(0)
	v_mfma_f32_16x16x32_bf16 v[124:127], v[154:157], v[212:215], v[124:127]
	v_mfma_f32_16x16x32_bf16 v[120:123], v[162:165], v[212:215], v[120:123]
	v_mfma_f32_16x16x32_bf16 v[104:107], v[162:165], v[220:223], v[104:107]
	v_mfma_f32_16x16x32_bf16 v[112:115], v[154:157], v[220:223], v[112:115]
	v_mfma_f32_16x16x32_bf16 v[96:99], v[154:157], v[228:231], v[96:99]
	v_mfma_f32_16x16x32_bf16 v[88:91], v[162:165], v[228:231], v[88:91]
	v_mfma_f32_16x16x32_bf16 v[72:75], v[162:165], v[236:239], v[72:75]
	v_mfma_f32_16x16x32_bf16 v[80:83], v[154:157], v[236:239], v[80:83]
	v_mfma_f32_16x16x32_bf16 v[124:127], v[158:161], v[216:219], v[124:127]
	v_mfma_f32_16x16x32_bf16 v[120:123], v[168:171], v[216:219], v[120:123]
	v_mfma_f32_16x16x32_bf16 v[104:107], v[168:171], v[224:227], v[104:107]
	v_mfma_f32_16x16x32_bf16 v[112:115], v[158:161], v[224:227], v[112:115]
	v_mfma_f32_16x16x32_bf16 v[96:99], v[158:161], v[232:235], v[96:99]
	v_mfma_f32_16x16x32_bf16 v[88:91], v[168:171], v[232:235], v[88:91]
	v_mfma_f32_16x16x32_bf16 v[72:75], v[168:171], v[240:243], v[72:75]
	v_mfma_f32_16x16x32_bf16 v[80:83], v[158:161], v[240:243], v[80:83]
	s_setprio 0
	s_setprio 1
	v_mfma_f32_16x16x32_bf16 v[116:119], v[172:175], v[212:215], v[116:119]
	v_mfma_f32_16x16x32_bf16 v[108:111], v[204:207], v[212:215], v[108:111]
	v_mfma_f32_16x16x32_bf16 v[92:95], v[204:207], v[220:223], v[92:95]
	v_mfma_f32_16x16x32_bf16 v[100:103], v[172:175], v[220:223], v[100:103]
	v_mfma_f32_16x16x32_bf16 v[84:87], v[172:175], v[228:231], v[84:87]
	v_mfma_f32_16x16x32_bf16 v[76:79], v[204:207], v[228:231], v[76:79]
	v_mfma_f32_16x16x32_bf16 v[64:67], v[204:207], v[236:239], v[64:67]
	v_mfma_f32_16x16x32_bf16 v[68:71], v[172:175], v[236:239], v[68:71]
	v_mfma_f32_16x16x32_bf16 v[116:119], v[176:179], v[216:219], v[116:119]
	v_mfma_f32_16x16x32_bf16 v[108:111], v[208:211], v[216:219], v[108:111]
	v_mfma_f32_16x16x32_bf16 v[92:95], v[208:211], v[224:227], v[92:95]
	v_mfma_f32_16x16x32_bf16 v[100:103], v[176:179], v[224:227], v[100:103]
	v_mfma_f32_16x16x32_bf16 v[84:87], v[176:179], v[232:235], v[84:87]
	v_mfma_f32_16x16x32_bf16 v[76:79], v[208:211], v[232:235], v[76:79]
	v_mfma_f32_16x16x32_bf16 v[64:67], v[208:211], v[240:243], v[64:67]
	v_mfma_f32_16x16x32_bf16 v[68:71], v[176:179], v[240:243], v[68:71]
	s_setprio 0
	s_barrier
	s_add_i32 s18, s40, s22
	v_lshl_add_u64 v[142:143], v[142:143], 0, s[48:49]
	s_mov_b32 m0, s18
	ds_read_b128 v[212:215], v141 offset:49152
	ds_read_b128 v[216:219], v141 offset:50176
	ds_read_b128 v[220:223], v141 offset:51200
	ds_read_b128 v[224:227], v141 offset:52224
	ds_read_b128 v[228:231], v141 offset:53248
	ds_read_b128 v[232:235], v141 offset:54272
	ds_read_b128 v[236:239], v141 offset:55296
	ds_read_b128 v[240:243], v141 offset:56320
	global_load_lds_dwordx4 v[142:143], off
	s_add_i32 m0, s18, 0x2000
	s_add_u32 s14, s14, 0x20080
	v_lshl_add_u64 v[142:143], v[180:181], 0, s[48:49]
	s_addc_u32 s15, s15, 0
	s_add_i32 s18, s41, s22
	global_load_lds_dwordx4 v[142:143], off
	v_lshl_add_u64 v[142:143], s[14:15], 0, v[144:145]
	s_mov_b32 m0, s18
	s_nop 0
	global_load_lds_dwordx4 v[142:143], off
	v_lshl_add_u64 v[142:143], s[14:15], 0, v[130:131]
	s_add_i32 m0, s18, 0x2000
	s_nop 0
	global_load_lds_dwordx4 v[142:143], off
	v_lshl_add_u64 v[142:143], v[190:191], 0, s[48:49]
	s_mov_b32 m0, s30
	s_nop 0
	global_load_lds_dwordx4 v[142:143], off
	v_lshl_add_u64 v[142:143], v[192:193], 0, s[48:49]
	s_mov_b32 m0, s31
	s_nop 0
	global_load_lds_dwordx4 v[142:143], off
	s_waitcnt vmcnt(8)
	s_waitcnt lgkmcnt(0)
	s_barrier
	s_setprio 1
	s_waitcnt lgkmcnt(0)
	v_mfma_f32_16x16x32_bf16 v[60:63], v[154:157], v[212:215], v[60:63]
	v_mfma_f32_16x16x32_bf16 v[56:59], v[162:165], v[212:215], v[56:59]
	v_mfma_f32_16x16x32_bf16 v[44:47], v[162:165], v[220:223], v[44:47]
	v_mfma_f32_16x16x32_bf16 v[52:55], v[154:157], v[220:223], v[52:55]
	v_mfma_f32_16x16x32_bf16 v[36:39], v[154:157], v[228:231], v[36:39]
	v_mfma_f32_16x16x32_bf16 v[28:31], v[162:165], v[228:231], v[28:31]
	v_mfma_f32_16x16x32_bf16 v[12:15], v[162:165], v[236:239], v[12:15]
	v_mfma_f32_16x16x32_bf16 v[20:23], v[154:157], v[236:239], v[20:23]
	v_mfma_f32_16x16x32_bf16 v[60:63], v[158:161], v[216:219], v[60:63]
	v_mfma_f32_16x16x32_bf16 v[56:59], v[168:171], v[216:219], v[56:59]
	v_mfma_f32_16x16x32_bf16 v[44:47], v[168:171], v[224:227], v[44:47]
	v_mfma_f32_16x16x32_bf16 v[52:55], v[158:161], v[224:227], v[52:55]
	v_mfma_f32_16x16x32_bf16 v[36:39], v[158:161], v[232:235], v[36:39]
	v_mfma_f32_16x16x32_bf16 v[28:31], v[168:171], v[232:235], v[28:31]
	v_mfma_f32_16x16x32_bf16 v[12:15], v[168:171], v[240:243], v[12:15]
	v_mfma_f32_16x16x32_bf16 v[20:23], v[158:161], v[240:243], v[20:23]
	s_setprio 0
	s_setprio 1
	v_mfma_f32_16x16x32_bf16 v[48:51], v[172:175], v[212:215], v[48:51]
	v_mfma_f32_16x16x32_bf16 v[40:43], v[204:207], v[212:215], v[40:43]
	v_mfma_f32_16x16x32_bf16 v[24:27], v[204:207], v[220:223], v[24:27]
	v_mfma_f32_16x16x32_bf16 v[32:35], v[172:175], v[220:223], v[32:35]
	v_mfma_f32_16x16x32_bf16 v[16:19], v[172:175], v[228:231], v[16:19]
	v_mfma_f32_16x16x32_bf16 v[8:11], v[204:207], v[228:231], v[8:11]
	v_mfma_f32_16x16x32_bf16 v[0:3], v[204:207], v[236:239], v[0:3]
	v_mfma_f32_16x16x32_bf16 v[4:7], v[172:175], v[236:239], v[4:7]
	v_mfma_f32_16x16x32_bf16 v[48:51], v[176:179], v[216:219], v[48:51]
	v_mfma_f32_16x16x32_bf16 v[40:43], v[208:211], v[216:219], v[40:43]
	v_mfma_f32_16x16x32_bf16 v[24:27], v[208:211], v[224:227], v[24:27]
	v_mfma_f32_16x16x32_bf16 v[32:35], v[176:179], v[224:227], v[32:35]
	v_mfma_f32_16x16x32_bf16 v[16:19], v[176:179], v[232:235], v[16:19]
	v_mfma_f32_16x16x32_bf16 v[8:11], v[208:211], v[232:235], v[8:11]
	v_mfma_f32_16x16x32_bf16 v[0:3], v[208:211], v[240:243], v[0:3]
	v_mfma_f32_16x16x32_bf16 v[4:7], v[176:179], v[240:243], v[4:7]
	s_setprio 0
	s_barrier
	s_add_i32 s37, s37, 2
	s_add_u32 s12, s12, 0x100
	s_addc_u32 s13, s13, 0
	s_cmp_gt_u32 s37, 5
	s_cbranch_scc0 .LBB0_987
	s_cmpk_lt_u32 s21, 0x100
	s_cbranch_scc0 .LBB0_990
	s_barrier

.LBB0_997:
	s_add_u32 s12, s31, s10
	s_addc_u32 s13, s33, s11
	s_add_u32 s12, s12, 0x1000100
	s_addc_u32 s13, s13, 0
	s_add_u32 s41, s36, s10
	s_addc_u32 s42, s37, s11
	s_add_i32 s43, 0, 0x10000
	s_cmpk_eq_i32 s10, 0x700
	s_cselect_b32 s15, s9, s13
	s_cselect_b32 s14, s8, s12
	v_add_u32_e32 v143, s43, v141
	s_cselect_b32 s13, s7, s42
	s_cselect_b32 s12, s6, s41
	s_add_i32 s41, 0, 0x14000
	ds_read_b128 v[154:157], v143
	ds_read_b128 v[158:161], v143 offset:1024
	ds_read_b128 v[162:165], v143 offset:2048
	ds_read_b128 v[168:171], v143 offset:3072
	v_add_u32_e32 v143, s41, v141
	ds_read_b128 v[172:175], v143
	ds_read_b128 v[176:179], v143 offset:1024
	ds_read_b128 v[204:207], v143 offset:2048
	ds_read_b128 v[208:211], v143 offset:3072
	v_lshl_add_u64 v[180:181], v[136:137], 0, s[10:11]
	s_add_i32 m0, s21, 0xc000
	ds_read_b128 v[212:215], v142
	ds_read_b128 v[216:219], v142 offset:1024
	ds_read_b128 v[220:223], v142 offset:2048
	ds_read_b128 v[224:227], v142 offset:3072
	ds_read_b128 v[228:231], v142 offset:4096
	ds_read_b128 v[232:235], v142 offset:5120
	ds_read_b128 v[236:239], v142 offset:6144
	ds_read_b128 v[240:243], v142 offset:7168
	global_load_lds_dwordx4 v[180:181], off
	v_lshl_add_u64 v[180:181], v[138:139], 0, s[10:11]
	s_add_i32 m0, s21, 0xe000
	s_nop 0
	global_load_lds_dwordx4 v[180:181], off
	s_waitcnt vmcnt(8)
	s_waitcnt lgkmcnt(0)
	s_barrier
	s_setprio 1
	s_waitcnt lgkmcnt(0)
	v_mfma_f32_16x16x32_bf16 v[124:127], v[154:157], v[212:215], v[124:127]
	v_mfma_f32_16x16x32_bf16 v[120:123], v[162:165], v[212:215], v[120:123]
	v_mfma_f32_16x16x32_bf16 v[104:107], v[162:165], v[220:223], v[104:107]
	v_mfma_f32_16x16x32_bf16 v[108:111], v[154:157], v[220:223], v[108:111]
	v_mfma_f32_16x16x32_bf16 v[92:95], v[154:157], v[228:231], v[92:95]
	v_mfma_f32_16x16x32_bf16 v[88:91], v[162:165], v[228:231], v[88:91]
	v_mfma_f32_16x16x32_bf16 v[72:75], v[162:165], v[236:239], v[72:75]
	v_mfma_f32_16x16x32_bf16 v[76:79], v[154:157], v[236:239], v[76:79]
	v_mfma_f32_16x16x32_bf16 v[124:127], v[158:161], v[216:219], v[124:127]
	v_mfma_f32_16x16x32_bf16 v[120:123], v[168:171], v[216:219], v[120:123]
	v_mfma_f32_16x16x32_bf16 v[104:107], v[168:171], v[224:227], v[104:107]
	v_mfma_f32_16x16x32_bf16 v[108:111], v[158:161], v[224:227], v[108:111]
	v_mfma_f32_16x16x32_bf16 v[92:95], v[158:161], v[232:235], v[92:95]
	v_mfma_f32_16x16x32_bf16 v[88:91], v[168:171], v[232:235], v[88:91]
	v_mfma_f32_16x16x32_bf16 v[72:75], v[168:171], v[240:243], v[72:75]
	v_mfma_f32_16x16x32_bf16 v[76:79], v[158:161], v[240:243], v[76:79]
	s_setprio 0
	s_setprio 1
	v_mfma_f32_16x16x32_bf16 v[116:119], v[172:175], v[212:215], v[116:119]
	v_mfma_f32_16x16x32_bf16 v[112:115], v[204:207], v[212:215], v[112:115]
	v_mfma_f32_16x16x32_bf16 v[96:99], v[204:207], v[220:223], v[96:99]
	v_mfma_f32_16x16x32_bf16 v[100:103], v[172:175], v[220:223], v[100:103]
	v_mfma_f32_16x16x32_bf16 v[84:87], v[172:175], v[228:231], v[84:87]
	v_mfma_f32_16x16x32_bf16 v[80:83], v[204:207], v[228:231], v[80:83]
	v_mfma_f32_16x16x32_bf16 v[64:67], v[204:207], v[236:239], v[64:67]
	v_mfma_f32_16x16x32_bf16 v[68:71], v[172:175], v[236:239], v[68:71]
	v_mfma_f32_16x16x32_bf16 v[116:119], v[176:179], v[216:219], v[116:119]
	v_mfma_f32_16x16x32_bf16 v[112:115], v[208:211], v[216:219], v[112:115]
	v_mfma_f32_16x16x32_bf16 v[96:99], v[208:211], v[224:227], v[96:99]
	v_mfma_f32_16x16x32_bf16 v[100:103], v[176:179], v[224:227], v[100:103]
	v_mfma_f32_16x16x32_bf16 v[84:87], v[176:179], v[232:235], v[84:87]
	v_mfma_f32_16x16x32_bf16 v[80:83], v[208:211], v[232:235], v[80:83]
	v_mfma_f32_16x16x32_bf16 v[64:67], v[208:211], v[240:243], v[64:67]
	v_mfma_f32_16x16x32_bf16 v[68:71], v[176:179], v[240:243], v[68:71]
	s_setprio 0
	s_barrier
	s_add_i32 s42, s43, s19
	v_lshl_add_u64 v[180:181], s[12:13], 0, v[144:145]
	s_mov_b32 m0, s42
	ds_read_b128 v[212:215], v142 offset:16384
	ds_read_b128 v[216:219], v142 offset:17408
	ds_read_b128 v[220:223], v142 offset:18432
	ds_read_b128 v[224:227], v142 offset:19456
	ds_read_b128 v[228:231], v142 offset:20480
	ds_read_b128 v[232:235], v142 offset:21504
	ds_read_b128 v[236:239], v142 offset:22528
	ds_read_b128 v[240:243], v142 offset:23552
	global_load_lds_dwordx4 v[180:181], off
	s_add_i32 m0, s42, 0x2000
	s_add_u32 s42, s12, 0x40000
	v_lshl_add_u64 v[190:191], s[12:13], 0, v[130:131]
	s_addc_u32 s43, s13, 0
	s_add_i32 s41, s41, s19
	global_load_lds_dwordx4 v[190:191], off
	v_lshl_add_u64 v[192:193], s[42:43], 0, v[144:145]
	s_mov_b32 m0, s41
	v_lshl_add_u64 v[244:245], s[14:15], 0, v[132:133]
	global_load_lds_dwordx4 v[192:193], off
	v_lshl_add_u64 v[192:193], s[42:43], 0, v[130:131]
	s_add_i32 m0, s41, 0x2000
	s_nop 0
	global_load_lds_dwordx4 v[192:193], off
	v_lshl_add_u64 v[192:193], s[14:15], 0, v[134:135]
	s_mov_b32 m0, s21
	s_nop 0
	global_load_lds_dwordx4 v[192:193], off
	s_mov_b32 m0, s22
	s_nop 0
	global_load_lds_dwordx4 v[244:245], off
	s_waitcnt vmcnt(8)
	s_waitcnt lgkmcnt(0)
	s_barrier
	s_setprio 1
	s_waitcnt lgkmcnt(0)
	v_mfma_f32_16x16x32_bf16 v[60:63], v[154:157], v[212:215], v[60:63]
	v_mfma_f32_16x16x32_bf16 v[56:59], v[162:165], v[212:215], v[56:59]
	v_mfma_f32_16x16x32_bf16 v[40:43], v[162:165], v[220:223], v[40:43]
	v_mfma_f32_16x16x32_bf16 v[44:47], v[154:157], v[220:223], v[44:47]
	v_mfma_f32_16x16x32_bf16 v[28:31], v[154:157], v[228:231], v[28:31]
	v_mfma_f32_16x16x32_bf16 v[24:27], v[162:165], v[228:231], v[24:27]
	v_mfma_f32_16x16x32_bf16 v[8:11], v[162:165], v[236:239], v[8:11]
	v_mfma_f32_16x16x32_bf16 v[12:15], v[154:157], v[236:239], v[12:15]
	v_mfma_f32_16x16x32_bf16 v[60:63], v[158:161], v[216:219], v[60:63]
	v_mfma_f32_16x16x32_bf16 v[56:59], v[168:171], v[216:219], v[56:59]
	v_mfma_f32_16x16x32_bf16 v[40:43], v[168:171], v[224:227], v[40:43]
	v_mfma_f32_16x16x32_bf16 v[44:47], v[158:161], v[224:227], v[44:47]
	v_mfma_f32_16x16x32_bf16 v[28:31], v[158:161], v[232:235], v[28:31]
	v_mfma_f32_16x16x32_bf16 v[24:27], v[168:171], v[232:235], v[24:27]
	v_mfma_f32_16x16x32_bf16 v[8:11], v[168:171], v[240:243], v[8:11]
	v_mfma_f32_16x16x32_bf16 v[12:15], v[158:161], v[240:243], v[12:15]
	s_setprio 0
	s_setprio 1
	v_mfma_f32_16x16x32_bf16 v[52:55], v[172:175], v[212:215], v[52:55]
	v_mfma_f32_16x16x32_bf16 v[48:51], v[204:207], v[212:215], v[48:51]
	v_mfma_f32_16x16x32_bf16 v[32:35], v[204:207], v[220:223], v[32:35]
	v_mfma_f32_16x16x32_bf16 v[36:39], v[172:175], v[220:223], v[36:39]
	v_mfma_f32_16x16x32_bf16 v[20:23], v[172:175], v[228:231], v[20:23]
	v_mfma_f32_16x16x32_bf16 v[16:19], v[204:207], v[228:231], v[16:19]
	v_mfma_f32_16x16x32_bf16 v[0:3], v[204:207], v[236:239], v[0:3]
	v_mfma_f32_16x16x32_bf16 v[4:7], v[172:175], v[236:239], v[4:7]
	v_mfma_f32_16x16x32_bf16 v[52:55], v[176:179], v[216:219], v[52:55]
	v_mfma_f32_16x16x32_bf16 v[48:51], v[208:211], v[216:219], v[48:51]
	v_mfma_f32_16x16x32_bf16 v[32:35], v[208:211], v[224:227], v[32:35]
	v_mfma_f32_16x16x32_bf16 v[36:39], v[176:179], v[224:227], v[36:39]
	v_mfma_f32_16x16x32_bf16 v[20:23], v[176:179], v[232:235], v[20:23]
	v_mfma_f32_16x16x32_bf16 v[16:19], v[208:211], v[232:235], v[16:19]
	v_mfma_f32_16x16x32_bf16 v[0:3], v[208:211], v[240:243], v[0:3]
	v_mfma_f32_16x16x32_bf16 v[4:7], v[176:179], v[240:243], v[4:7]
	s_setprio 0
	s_barrier
	s_add_i32 s41, 0, 0x18000
	v_add_u32_e32 v143, s41, v141
	s_add_i32 s42, 0, 0x1c000
	ds_read_b128 v[154:157], v143
	ds_read_b128 v[158:161], v143 offset:1024
	ds_read_b128 v[162:165], v143 offset:2048
	ds_read_b128 v[168:171], v143 offset:3072
	v_add_u32_e32 v143, s42, v141
	ds_read_b128 v[172:175], v143
	ds_read_b128 v[176:179], v143 offset:1024
	ds_read_b128 v[204:207], v143 offset:2048
	ds_read_b128 v[208:211], v143 offset:3072
	s_add_u32 s14, s14, 0x40000
	s_addc_u32 s15, s15, 0
	s_mov_b32 m0, s23
	v_lshl_add_u64 v[246:247], s[14:15], 0, v[134:135]
	ds_read_b128 v[212:215], v142 offset:32768
	ds_read_b128 v[216:219], v142 offset:33792
	ds_read_b128 v[220:223], v142 offset:34816
	ds_read_b128 v[224:227], v142 offset:35840
	ds_read_b128 v[228:231], v142 offset:36864
	ds_read_b128 v[232:235], v142 offset:37888
	ds_read_b128 v[236:239], v142 offset:38912
	ds_read_b128 v[240:243], v142 offset:39936
	global_load_lds_dwordx4 v[246:247], off
	v_lshl_add_u64 v[246:247], s[14:15], 0, v[132:133]
	s_mov_b32 m0, s25
	s_nop 0
	global_load_lds_dwordx4 v[246:247], off
	s_waitcnt vmcnt(8)
	s_waitcnt lgkmcnt(0)
	s_barrier
	s_setprio 1
	s_waitcnt lgkmcnt(0)
	v_mfma_f32_16x16x32_bf16 v[124:127], v[154:157], v[212:215], v[124:127]
	v_mfma_f32_16x16x32_bf16 v[120:123], v[162:165], v[212:215], v[120:123]
	v_mfma_f32_16x16x32_bf16 v[104:107], v[162:165], v[220:223], v[104:107]
	v_mfma_f32_16x16x32_bf16 v[108:111], v[154:157], v[220:223], v[108:111]
	v_mfma_f32_16x16x32_bf16 v[92:95], v[154:157], v[228:231], v[92:95]
	v_mfma_f32_16x16x32_bf16 v[88:91], v[162:165], v[228:231], v[88:91]
	v_mfma_f32_16x16x32_bf16 v[72:75], v[162:165], v[236:239], v[72:75]
	v_mfma_f32_16x16x32_bf16 v[76:79], v[154:157], v[236:239], v[76:79]
	v_mfma_f32_16x16x32_bf16 v[124:127], v[158:161], v[216:219], v[124:127]
	v_mfma_f32_16x16x32_bf16 v[120:123], v[168:171], v[216:219], v[120:123]
	v_mfma_f32_16x16x32_bf16 v[104:107], v[168:171], v[224:227], v[104:107]
	v_mfma_f32_16x16x32_bf16 v[108:111], v[158:161], v[224:227], v[108:111]
	v_mfma_f32_16x16x32_bf16 v[92:95], v[158:161], v[232:235], v[92:95]
	v_mfma_f32_16x16x32_bf16 v[88:91], v[168:171], v[232:235], v[88:91]
	v_mfma_f32_16x16x32_bf16 v[72:75], v[168:171], v[240:243], v[72:75]
	v_mfma_f32_16x16x32_bf16 v[76:79], v[158:161], v[240:243], v[76:79]
	s_setprio 0
	s_setprio 1
	v_mfma_f32_16x16x32_bf16 v[116:119], v[172:175], v[212:215], v[116:119]
	v_mfma_f32_16x16x32_bf16 v[112:115], v[204:207], v[212:215], v[112:115]
	v_mfma_f32_16x16x32_bf16 v[96:99], v[204:207], v[220:223], v[96:99]
	v_mfma_f32_16x16x32_bf16 v[100:103], v[172:175], v[220:223], v[100:103]
	v_mfma_f32_16x16x32_bf16 v[84:87], v[172:175], v[228:231], v[84:87]
	v_mfma_f32_16x16x32_bf16 v[80:83], v[204:207], v[228:231], v[80:83]
	v_mfma_f32_16x16x32_bf16 v[64:67], v[204:207], v[236:239], v[64:67]
	v_mfma_f32_16x16x32_bf16 v[68:71], v[172:175], v[236:239], v[68:71]
	v_mfma_f32_16x16x32_bf16 v[116:119], v[176:179], v[216:219], v[116:119]
	v_mfma_f32_16x16x32_bf16 v[112:115], v[208:211], v[216:219], v[112:115]
	v_mfma_f32_16x16x32_bf16 v[96:99], v[208:211], v[224:227], v[96:99]
	v_mfma_f32_16x16x32_bf16 v[100:103], v[176:179], v[224:227], v[100:103]
	v_mfma_f32_16x16x32_bf16 v[84:87], v[176:179], v[232:235], v[84:87]
	v_mfma_f32_16x16x32_bf16 v[80:83], v[208:211], v[232:235], v[80:83]
	v_mfma_f32_16x16x32_bf16 v[64:67], v[208:211], v[240:243], v[64:67]
	v_mfma_f32_16x16x32_bf16 v[68:71], v[176:179], v[240:243], v[68:71]
	s_setprio 0
	s_barrier
	s_add_i32 s14, s41, s19
	v_lshl_add_u64 v[180:181], v[180:181], 0, s[48:49]
	s_mov_b32 m0, s14
	ds_read_b128 v[212:215], v142 offset:49152
	ds_read_b128 v[216:219], v142 offset:50176
	ds_read_b128 v[220:223], v142 offset:51200
	ds_read_b128 v[224:227], v142 offset:52224
	ds_read_b128 v[228:231], v142 offset:53248
	ds_read_b128 v[232:235], v142 offset:54272
	ds_read_b128 v[236:239], v142 offset:55296
	ds_read_b128 v[240:243], v142 offset:56320
	global_load_lds_dwordx4 v[180:181], off
	s_add_i32 m0, s14, 0x2000
	s_add_u32 s12, s12, 0x40080
	v_lshl_add_u64 v[180:181], v[190:191], 0, s[48:49]
	s_addc_u32 s13, s13, 0
	s_add_i32 s14, s42, s19
	global_load_lds_dwordx4 v[180:181], off
	v_lshl_add_u64 v[180:181], s[12:13], 0, v[144:145]
	s_mov_b32 m0, s14
	s_nop 0
	global_load_lds_dwordx4 v[180:181], off
	v_lshl_add_u64 v[180:181], s[12:13], 0, v[130:131]
	s_add_i32 m0, s14, 0x2000
	s_nop 0
	global_load_lds_dwordx4 v[180:181], off
	v_lshl_add_u64 v[180:181], v[192:193], 0, s[48:49]
	s_mov_b32 m0, s27
	s_nop 0
	global_load_lds_dwordx4 v[180:181], off
	v_lshl_add_u64 v[180:181], v[244:245], 0, s[48:49]
	s_mov_b32 m0, s30
	s_nop 0
	global_load_lds_dwordx4 v[180:181], off
	s_waitcnt vmcnt(8)
	s_waitcnt lgkmcnt(0)
	s_barrier
	s_setprio 1
	s_waitcnt lgkmcnt(0)
	v_mfma_f32_16x16x32_bf16 v[60:63], v[154:157], v[212:215], v[60:63]
	v_mfma_f32_16x16x32_bf16 v[56:59], v[162:165], v[212:215], v[56:59]
	v_mfma_f32_16x16x32_bf16 v[40:43], v[162:165], v[220:223], v[40:43]
	v_mfma_f32_16x16x32_bf16 v[44:47], v[154:157], v[220:223], v[44:47]
	v_mfma_f32_16x16x32_bf16 v[28:31], v[154:157], v[228:231], v[28:31]
	v_mfma_f32_16x16x32_bf16 v[24:27], v[162:165], v[228:231], v[24:27]
	v_mfma_f32_16x16x32_bf16 v[8:11], v[162:165], v[236:239], v[8:11]
	v_mfma_f32_16x16x32_bf16 v[12:15], v[154:157], v[236:239], v[12:15]
	v_mfma_f32_16x16x32_bf16 v[60:63], v[158:161], v[216:219], v[60:63]
	v_mfma_f32_16x16x32_bf16 v[56:59], v[168:171], v[216:219], v[56:59]
	v_mfma_f32_16x16x32_bf16 v[40:43], v[168:171], v[224:227], v[40:43]
	v_mfma_f32_16x16x32_bf16 v[44:47], v[158:161], v[224:227], v[44:47]
	v_mfma_f32_16x16x32_bf16 v[28:31], v[158:161], v[232:235], v[28:31]
	v_mfma_f32_16x16x32_bf16 v[24:27], v[168:171], v[232:235], v[24:27]
	v_mfma_f32_16x16x32_bf16 v[8:11], v[168:171], v[240:243], v[8:11]
	v_mfma_f32_16x16x32_bf16 v[12:15], v[158:161], v[240:243], v[12:15]
	s_setprio 0
	s_setprio 1
	v_mfma_f32_16x16x32_bf16 v[52:55], v[172:175], v[212:215], v[52:55]
	v_mfma_f32_16x16x32_bf16 v[48:51], v[204:207], v[212:215], v[48:51]
	v_mfma_f32_16x16x32_bf16 v[32:35], v[204:207], v[220:223], v[32:35]
	v_mfma_f32_16x16x32_bf16 v[36:39], v[172:175], v[220:223], v[36:39]
	v_mfma_f32_16x16x32_bf16 v[20:23], v[172:175], v[228:231], v[20:23]
	v_mfma_f32_16x16x32_bf16 v[16:19], v[204:207], v[228:231], v[16:19]
	v_mfma_f32_16x16x32_bf16 v[0:3], v[204:207], v[236:239], v[0:3]
	v_mfma_f32_16x16x32_bf16 v[4:7], v[172:175], v[236:239], v[4:7]
	v_mfma_f32_16x16x32_bf16 v[52:55], v[176:179], v[216:219], v[52:55]
	v_mfma_f32_16x16x32_bf16 v[48:51], v[208:211], v[216:219], v[48:51]
	v_mfma_f32_16x16x32_bf16 v[32:35], v[208:211], v[224:227], v[32:35]
	v_mfma_f32_16x16x32_bf16 v[36:39], v[176:179], v[224:227], v[36:39]
	v_mfma_f32_16x16x32_bf16 v[20:23], v[176:179], v[232:235], v[20:23]
	v_mfma_f32_16x16x32_bf16 v[16:19], v[208:211], v[232:235], v[16:19]
	v_mfma_f32_16x16x32_bf16 v[0:3], v[208:211], v[240:243], v[0:3]
	v_mfma_f32_16x16x32_bf16 v[4:7], v[176:179], v[240:243], v[4:7]
	s_setprio 0
	s_barrier
	s_add_i32 s40, s40, 2
	s_add_u32 s10, s10, 0x100
	s_addc_u32 s11, s11, 0
	s_cmp_gt_u32 s40, 13
	s_cbranch_scc0 .LBB0_997
	s_cmpk_lt_u32 s18, 0x100
	s_cbranch_scc0 .LBB0_1000
	s_barrier

.LBB0_1162:
	s_add_u32 s42, s56, 0xfffc0080
	s_addc_u32 s43, s57, -1
	s_add_i32 s60, 0, 0x10000
	s_cmp_eq_u32 s59, 4
	s_cselect_b32 s55, s15, s43
	s_cselect_b32 s54, s17, s42
	v_add_u32_e32 v140, s60, v143
	s_cselect_b32 s43, s13, s58
	s_cselect_b32 s42, s25, s53
	s_add_i32 s62, 0, 0x14000
	ds_read_b128 v[156:159], v140
	ds_read_b128 v[160:163], v140 offset:1024
	ds_read_b128 v[164:167], v140 offset:2048
	ds_read_b128 v[168:171], v140 offset:3072
	v_add_u32_e32 v140, s62, v143
	ds_read_b128 v[172:175], v140
	ds_read_b128 v[176:179], v140 offset:1024
	ds_read_b128 v[204:207], v140 offset:2048
	ds_read_b128 v[208:211], v140 offset:3072
	v_lshl_add_u64 v[140:141], s[56:57], 0, v[136:137]
	s_add_i32 m0, s23, 0xc000
	ds_read_b128 v[212:215], v154
	ds_read_b128 v[216:219], v154 offset:1024
	ds_read_b128 v[220:223], v154 offset:2048
	ds_read_b128 v[224:227], v154 offset:3072
	ds_read_b128 v[228:231], v154 offset:4096
	ds_read_b128 v[232:235], v154 offset:5120
	ds_read_b128 v[236:239], v154 offset:6144
	ds_read_b128 v[240:243], v154 offset:7168
	global_load_lds_dwordx4 v[140:141], off
	v_lshl_add_u64 v[140:141], s[56:57], 0, v[138:139]
	s_add_i32 m0, s23, 0xe000
	s_nop 0
	global_load_lds_dwordx4 v[140:141], off
	s_waitcnt vmcnt(8)
	s_waitcnt lgkmcnt(0)
	s_barrier
	s_setprio 1
	s_waitcnt lgkmcnt(0)
	v_mfma_f32_16x16x32_bf16 v[124:127], v[156:159], v[212:215], v[124:127]
	v_mfma_f32_16x16x32_bf16 v[120:123], v[164:167], v[212:215], v[120:123]
	v_mfma_f32_16x16x32_bf16 v[108:111], v[164:167], v[220:223], v[108:111]
	v_mfma_f32_16x16x32_bf16 v[116:119], v[156:159], v[220:223], v[116:119]
	v_mfma_f32_16x16x32_bf16 v[100:103], v[156:159], v[228:231], v[100:103]
	v_mfma_f32_16x16x32_bf16 v[92:95], v[164:167], v[228:231], v[92:95]
	v_mfma_f32_16x16x32_bf16 v[76:79], v[164:167], v[236:239], v[76:79]
	v_mfma_f32_16x16x32_bf16 v[84:87], v[156:159], v[236:239], v[84:87]
	v_mfma_f32_16x16x32_bf16 v[124:127], v[160:163], v[216:219], v[124:127]
	v_mfma_f32_16x16x32_bf16 v[120:123], v[168:171], v[216:219], v[120:123]
	v_mfma_f32_16x16x32_bf16 v[108:111], v[168:171], v[224:227], v[108:111]
	v_mfma_f32_16x16x32_bf16 v[116:119], v[160:163], v[224:227], v[116:119]
	v_mfma_f32_16x16x32_bf16 v[100:103], v[160:163], v[232:235], v[100:103]
	v_mfma_f32_16x16x32_bf16 v[92:95], v[168:171], v[232:235], v[92:95]
	v_mfma_f32_16x16x32_bf16 v[76:79], v[168:171], v[240:243], v[76:79]
	v_mfma_f32_16x16x32_bf16 v[84:87], v[160:163], v[240:243], v[84:87]
	s_setprio 0
	s_setprio 1
	v_mfma_f32_16x16x32_bf16 v[112:115], v[172:175], v[212:215], v[112:115]
	v_mfma_f32_16x16x32_bf16 v[104:107], v[204:207], v[212:215], v[104:107]
	v_mfma_f32_16x16x32_bf16 v[88:91], v[204:207], v[220:223], v[88:91]
	v_mfma_f32_16x16x32_bf16 v[96:99], v[172:175], v[220:223], v[96:99]
	v_mfma_f32_16x16x32_bf16 v[80:83], v[172:175], v[228:231], v[80:83]
	v_mfma_f32_16x16x32_bf16 v[72:75], v[204:207], v[228:231], v[72:75]
	v_mfma_f32_16x16x32_bf16 v[64:67], v[204:207], v[236:239], v[64:67]
	v_mfma_f32_16x16x32_bf16 v[68:71], v[172:175], v[236:239], v[68:71]
	v_mfma_f32_16x16x32_bf16 v[112:115], v[176:179], v[216:219], v[112:115]
	v_mfma_f32_16x16x32_bf16 v[104:107], v[208:211], v[216:219], v[104:107]
	v_mfma_f32_16x16x32_bf16 v[88:91], v[208:211], v[224:227], v[88:91]
	v_mfma_f32_16x16x32_bf16 v[96:99], v[176:179], v[224:227], v[96:99]
	v_mfma_f32_16x16x32_bf16 v[80:83], v[176:179], v[232:235], v[80:83]
	v_mfma_f32_16x16x32_bf16 v[72:75], v[208:211], v[232:235], v[72:75]
	v_mfma_f32_16x16x32_bf16 v[64:67], v[208:211], v[240:243], v[64:67]
	v_mfma_f32_16x16x32_bf16 v[68:71], v[176:179], v[240:243], v[68:71]
	s_setprio 0
	s_barrier
	s_add_i32 s60, s60, s36
	v_lshl_add_u64 v[140:141], s[42:43], 0, v[130:131]
	s_mov_b32 m0, s60
	ds_read_b128 v[212:215], v154 offset:16384
	ds_read_b128 v[216:219], v154 offset:17408
	ds_read_b128 v[220:223], v154 offset:18432
	ds_read_b128 v[224:227], v154 offset:19456
	ds_read_b128 v[228:231], v154 offset:20480
	ds_read_b128 v[232:235], v154 offset:21504
	ds_read_b128 v[236:239], v154 offset:22528
	ds_read_b128 v[240:243], v154 offset:23552
	global_load_lds_dwordx4 v[140:141], off
	s_add_i32 m0, s60, 0x2000
	s_add_u32 s60, s42, 0x40000
	v_lshl_add_u64 v[180:181], s[42:43], 0, v[134:135]
	s_addc_u32 s61, s43, 0
	s_add_i32 s62, s62, s36
	global_load_lds_dwordx4 v[180:181], off
	v_lshl_add_u64 v[190:191], s[60:61], 0, v[130:131]
	s_mov_b32 m0, s62
	v_lshl_add_u64 v[192:193], s[54:55], 0, v[132:133]
	global_load_lds_dwordx4 v[190:191], off
	v_lshl_add_u64 v[190:191], s[60:61], 0, v[134:135]
	s_add_i32 m0, s62, 0x2000
	s_nop 0
	global_load_lds_dwordx4 v[190:191], off
	v_lshl_add_u64 v[190:191], s[54:55], 0, v[128:129]
	s_mov_b32 m0, s23
	s_nop 0
	global_load_lds_dwordx4 v[190:191], off
	s_mov_b32 m0, s37
	s_nop 0
	global_load_lds_dwordx4 v[192:193], off
	s_waitcnt vmcnt(8)
	s_waitcnt lgkmcnt(0)
	s_barrier
	s_setprio 1
	s_waitcnt lgkmcnt(0)
	v_mfma_f32_16x16x32_bf16 v[60:63], v[156:159], v[212:215], v[60:63]
	v_mfma_f32_16x16x32_bf16 v[56:59], v[164:167], v[212:215], v[56:59]
	v_mfma_f32_16x16x32_bf16 v[44:47], v[164:167], v[220:223], v[44:47]
	v_mfma_f32_16x16x32_bf16 v[52:55], v[156:159], v[220:223], v[52:55]
	v_mfma_f32_16x16x32_bf16 v[36:39], v[156:159], v[228:231], v[36:39]
	v_mfma_f32_16x16x32_bf16 v[28:31], v[164:167], v[228:231], v[28:31]
	v_mfma_f32_16x16x32_bf16 v[12:15], v[164:167], v[236:239], v[12:15]
	v_mfma_f32_16x16x32_bf16 v[20:23], v[156:159], v[236:239], v[20:23]
	v_mfma_f32_16x16x32_bf16 v[60:63], v[160:163], v[216:219], v[60:63]
	v_mfma_f32_16x16x32_bf16 v[56:59], v[168:171], v[216:219], v[56:59]
	v_mfma_f32_16x16x32_bf16 v[44:47], v[168:171], v[224:227], v[44:47]
	v_mfma_f32_16x16x32_bf16 v[52:55], v[160:163], v[224:227], v[52:55]
	v_mfma_f32_16x16x32_bf16 v[36:39], v[160:163], v[232:235], v[36:39]
	v_mfma_f32_16x16x32_bf16 v[28:31], v[168:171], v[232:235], v[28:31]
	v_mfma_f32_16x16x32_bf16 v[12:15], v[168:171], v[240:243], v[12:15]
	v_mfma_f32_16x16x32_bf16 v[20:23], v[160:163], v[240:243], v[20:23]
	s_setprio 0
	s_setprio 1
	v_mfma_f32_16x16x32_bf16 v[48:51], v[172:175], v[212:215], v[48:51]
	v_mfma_f32_16x16x32_bf16 v[40:43], v[204:207], v[212:215], v[40:43]
	v_mfma_f32_16x16x32_bf16 v[24:27], v[204:207], v[220:223], v[24:27]
	v_mfma_f32_16x16x32_bf16 v[32:35], v[172:175], v[220:223], v[32:35]
	v_mfma_f32_16x16x32_bf16 v[16:19], v[172:175], v[228:231], v[16:19]
	v_mfma_f32_16x16x32_bf16 v[8:11], v[204:207], v[228:231], v[8:11]
	v_mfma_f32_16x16x32_bf16 v[0:3], v[204:207], v[236:239], v[0:3]
	v_mfma_f32_16x16x32_bf16 v[4:7], v[172:175], v[236:239], v[4:7]
	v_mfma_f32_16x16x32_bf16 v[48:51], v[176:179], v[216:219], v[48:51]
	v_mfma_f32_16x16x32_bf16 v[40:43], v[208:211], v[216:219], v[40:43]
	v_mfma_f32_16x16x32_bf16 v[24:27], v[208:211], v[224:227], v[24:27]
	v_mfma_f32_16x16x32_bf16 v[32:35], v[176:179], v[224:227], v[32:35]
	v_mfma_f32_16x16x32_bf16 v[16:19], v[176:179], v[232:235], v[16:19]
	v_mfma_f32_16x16x32_bf16 v[8:11], v[208:211], v[232:235], v[8:11]
	v_mfma_f32_16x16x32_bf16 v[0:3], v[208:211], v[240:243], v[0:3]
	v_mfma_f32_16x16x32_bf16 v[4:7], v[176:179], v[240:243], v[4:7]
	s_setprio 0
	s_barrier
	s_add_i32 s60, 0, 0x18000
	v_add_u32_e32 v155, s60, v143
	s_add_i32 s61, 0, 0x1c000
	ds_read_b128 v[156:159], v155
	ds_read_b128 v[160:163], v155 offset:1024
	ds_read_b128 v[164:167], v155 offset:2048
	ds_read_b128 v[168:171], v155 offset:3072
	v_add_u32_e32 v155, s61, v143
	ds_read_b128 v[172:175], v155
	ds_read_b128 v[176:179], v155 offset:1024
	ds_read_b128 v[204:207], v155 offset:2048
	ds_read_b128 v[208:211], v155 offset:3072
	s_add_u32 s54, s54, 0x40000
	s_addc_u32 s55, s55, 0
	s_mov_b32 m0, s40
	v_lshl_add_u64 v[244:245], s[54:55], 0, v[128:129]
	ds_read_b128 v[212:215], v154 offset:32768
	ds_read_b128 v[216:219], v154 offset:33792
	ds_read_b128 v[220:223], v154 offset:34816
	ds_read_b128 v[224:227], v154 offset:35840
	ds_read_b128 v[228:231], v154 offset:36864
	ds_read_b128 v[232:235], v154 offset:37888
	ds_read_b128 v[236:239], v154 offset:38912
	ds_read_b128 v[240:243], v154 offset:39936
	global_load_lds_dwordx4 v[244:245], off
	v_lshl_add_u64 v[244:245], s[54:55], 0, v[132:133]
	s_mov_b32 m0, s41
	s_nop 0
	global_load_lds_dwordx4 v[244:245], off
	s_waitcnt vmcnt(8)
	s_waitcnt lgkmcnt(0)
	s_barrier
	s_setprio 1
	s_waitcnt lgkmcnt(0)
	v_mfma_f32_16x16x32_bf16 v[124:127], v[156:159], v[212:215], v[124:127]
	v_mfma_f32_16x16x32_bf16 v[120:123], v[164:167], v[212:215], v[120:123]
	v_mfma_f32_16x16x32_bf16 v[108:111], v[164:167], v[220:223], v[108:111]
	v_mfma_f32_16x16x32_bf16 v[116:119], v[156:159], v[220:223], v[116:119]
	v_mfma_f32_16x16x32_bf16 v[100:103], v[156:159], v[228:231], v[100:103]
	v_mfma_f32_16x16x32_bf16 v[92:95], v[164:167], v[228:231], v[92:95]
	v_mfma_f32_16x16x32_bf16 v[76:79], v[164:167], v[236:239], v[76:79]
	v_mfma_f32_16x16x32_bf16 v[84:87], v[156:159], v[236:239], v[84:87]
	v_mfma_f32_16x16x32_bf16 v[124:127], v[160:163], v[216:219], v[124:127]
	v_mfma_f32_16x16x32_bf16 v[120:123], v[168:171], v[216:219], v[120:123]
	v_mfma_f32_16x16x32_bf16 v[108:111], v[168:171], v[224:227], v[108:111]
	v_mfma_f32_16x16x32_bf16 v[116:119], v[160:163], v[224:227], v[116:119]
	v_mfma_f32_16x16x32_bf16 v[100:103], v[160:163], v[232:235], v[100:103]
	v_mfma_f32_16x16x32_bf16 v[92:95], v[168:171], v[232:235], v[92:95]
	v_mfma_f32_16x16x32_bf16 v[76:79], v[168:171], v[240:243], v[76:79]
	v_mfma_f32_16x16x32_bf16 v[84:87], v[160:163], v[240:243], v[84:87]
	s_setprio 0
	s_setprio 1
	v_mfma_f32_16x16x32_bf16 v[112:115], v[172:175], v[212:215], v[112:115]
	v_mfma_f32_16x16x32_bf16 v[104:107], v[204:207], v[212:215], v[104:107]
	v_mfma_f32_16x16x32_bf16 v[88:91], v[204:207], v[220:223], v[88:91]
	v_mfma_f32_16x16x32_bf16 v[96:99], v[172:175], v[220:223], v[96:99]
	v_mfma_f32_16x16x32_bf16 v[80:83], v[172:175], v[228:231], v[80:83]
	v_mfma_f32_16x16x32_bf16 v[72:75], v[204:207], v[228:231], v[72:75]
	v_mfma_f32_16x16x32_bf16 v[64:67], v[204:207], v[236:239], v[64:67]
	v_mfma_f32_16x16x32_bf16 v[68:71], v[172:175], v[236:239], v[68:71]
	v_mfma_f32_16x16x32_bf16 v[112:115], v[176:179], v[216:219], v[112:115]
	v_mfma_f32_16x16x32_bf16 v[104:107], v[208:211], v[216:219], v[104:107]
	v_mfma_f32_16x16x32_bf16 v[88:91], v[208:211], v[224:227], v[88:91]
	v_mfma_f32_16x16x32_bf16 v[96:99], v[176:179], v[224:227], v[96:99]
	v_mfma_f32_16x16x32_bf16 v[80:83], v[176:179], v[232:235], v[80:83]
	v_mfma_f32_16x16x32_bf16 v[72:75], v[208:211], v[232:235], v[72:75]
	v_mfma_f32_16x16x32_bf16 v[64:67], v[208:211], v[240:243], v[64:67]
	v_mfma_f32_16x16x32_bf16 v[68:71], v[176:179], v[240:243], v[68:71]
	s_setprio 0
	s_barrier
	s_add_i32 s54, s60, s36
	v_lshl_add_u64 v[140:141], v[140:141], 0, s[48:49]
	s_mov_b32 m0, s54
	ds_read_b128 v[212:215], v154 offset:49152
	ds_read_b128 v[216:219], v154 offset:50176
	ds_read_b128 v[220:223], v154 offset:51200
	ds_read_b128 v[224:227], v154 offset:52224
	ds_read_b128 v[228:231], v154 offset:53248
	ds_read_b128 v[232:235], v154 offset:54272
	ds_read_b128 v[236:239], v154 offset:55296
	ds_read_b128 v[240:243], v154 offset:56320
	global_load_lds_dwordx4 v[140:141], off
	s_add_i32 m0, s54, 0x2000
	s_add_u32 s42, s42, 0x40080
	v_lshl_add_u64 v[140:141], v[180:181], 0, s[48:49]
	s_addc_u32 s43, s43, 0
	s_add_i32 s54, s61, s36
	global_load_lds_dwordx4 v[140:141], off
	v_lshl_add_u64 v[140:141], s[42:43], 0, v[130:131]
	s_mov_b32 m0, s54
	s_nop 0
	global_load_lds_dwordx4 v[140:141], off
	v_lshl_add_u64 v[140:141], s[42:43], 0, v[134:135]
	s_add_i32 m0, s54, 0x2000
	s_nop 0
	global_load_lds_dwordx4 v[140:141], off
	v_lshl_add_u64 v[140:141], v[190:191], 0, s[48:49]
	s_mov_b32 m0, s44
	s_nop 0
	global_load_lds_dwordx4 v[140:141], off
	v_lshl_add_u64 v[140:141], v[192:193], 0, s[48:49]
	s_mov_b32 m0, s45
	s_nop 0
	global_load_lds_dwordx4 v[140:141], off
	s_waitcnt vmcnt(8)
	s_waitcnt lgkmcnt(0)
	s_barrier
	s_setprio 1
	s_waitcnt lgkmcnt(0)
	v_mfma_f32_16x16x32_bf16 v[60:63], v[156:159], v[212:215], v[60:63]
	v_mfma_f32_16x16x32_bf16 v[56:59], v[164:167], v[212:215], v[56:59]
	v_mfma_f32_16x16x32_bf16 v[44:47], v[164:167], v[220:223], v[44:47]
	v_mfma_f32_16x16x32_bf16 v[52:55], v[156:159], v[220:223], v[52:55]
	v_mfma_f32_16x16x32_bf16 v[36:39], v[156:159], v[228:231], v[36:39]
	v_mfma_f32_16x16x32_bf16 v[28:31], v[164:167], v[228:231], v[28:31]
	v_mfma_f32_16x16x32_bf16 v[12:15], v[164:167], v[236:239], v[12:15]
	v_mfma_f32_16x16x32_bf16 v[20:23], v[156:159], v[236:239], v[20:23]
	v_mfma_f32_16x16x32_bf16 v[60:63], v[160:163], v[216:219], v[60:63]
	v_mfma_f32_16x16x32_bf16 v[56:59], v[168:171], v[216:219], v[56:59]
	v_mfma_f32_16x16x32_bf16 v[44:47], v[168:171], v[224:227], v[44:47]
	v_mfma_f32_16x16x32_bf16 v[52:55], v[160:163], v[224:227], v[52:55]
	v_mfma_f32_16x16x32_bf16 v[36:39], v[160:163], v[232:235], v[36:39]
	v_mfma_f32_16x16x32_bf16 v[28:31], v[168:171], v[232:235], v[28:31]
	v_mfma_f32_16x16x32_bf16 v[12:15], v[168:171], v[240:243], v[12:15]
	v_mfma_f32_16x16x32_bf16 v[20:23], v[160:163], v[240:243], v[20:23]
	s_setprio 0
	s_setprio 1
	v_mfma_f32_16x16x32_bf16 v[48:51], v[172:175], v[212:215], v[48:51]
	v_mfma_f32_16x16x32_bf16 v[40:43], v[204:207], v[212:215], v[40:43]
	v_mfma_f32_16x16x32_bf16 v[24:27], v[204:207], v[220:223], v[24:27]
	v_mfma_f32_16x16x32_bf16 v[32:35], v[172:175], v[220:223], v[32:35]
	v_mfma_f32_16x16x32_bf16 v[16:19], v[172:175], v[228:231], v[16:19]
	v_mfma_f32_16x16x32_bf16 v[8:11], v[204:207], v[228:231], v[8:11]
	v_mfma_f32_16x16x32_bf16 v[0:3], v[204:207], v[236:239], v[0:3]
	v_mfma_f32_16x16x32_bf16 v[4:7], v[172:175], v[236:239], v[4:7]
	v_mfma_f32_16x16x32_bf16 v[48:51], v[176:179], v[216:219], v[48:51]
	v_mfma_f32_16x16x32_bf16 v[40:43], v[208:211], v[216:219], v[40:43]
	v_mfma_f32_16x16x32_bf16 v[24:27], v[208:211], v[224:227], v[24:27]
	v_mfma_f32_16x16x32_bf16 v[32:35], v[176:179], v[224:227], v[32:35]
	v_mfma_f32_16x16x32_bf16 v[16:19], v[176:179], v[232:235], v[16:19]
	v_mfma_f32_16x16x32_bf16 v[8:11], v[208:211], v[232:235], v[8:11]
	v_mfma_f32_16x16x32_bf16 v[0:3], v[208:211], v[240:243], v[0:3]
	v_mfma_f32_16x16x32_bf16 v[4:7], v[176:179], v[240:243], v[4:7]
	s_setprio 0
	s_barrier
	s_add_i32 s59, s59, 2
	s_add_u32 s56, s56, 0x100
	s_addc_u32 s57, s57, 0
	s_add_u32 s53, s53, 0x100
	s_addc_u32 s58, s58, 0
	s_cmp_gt_u32 s59, 5
	s_cbranch_scc0 .LBB0_1162
	s_and_b64 vcc, exec, s[10:11]
	s_cbranch_vccz .LBB0_1165
	s_barrier
